# G9 layer-0 tail round: 32 ctx units split 4-way along K into 128 quarter-units; f32 partials to dead CAT scratch, release/atomic/acquire, last arriver sums 4 partials in fixed order then runs normal e
# speedup vs baseline: 1.0098x; 1.0098x over previous
;     DI bool next(int i, Unit& u) const { const int L = (i0 + i) * G + c - start; if (L >= 144) return false; const int bt = L >> 2; u.pm = L & 3; u.pn = (bt / 9) * 16 + (bt % 9); u.kob = 256 * u.pm; return true; }
;     DI bool next(int i, Unit& u) const {
;         const long L = (long)(i0 + i) * G + c - start; if (L >= cnt) return false;
;         const int w = (int)L, nig = 8 * nN, gid = w / nig, fm = gid * 8, gsz = (nM - fm) < 8 ? (nM - fm) : 8;
;         u.pm = fm + ((w % nig) % gsz); u.pn = (w % nig) / gsz; u.kob = kobm * u.pm; return true;
;     }
.LBB0_1698:
	s_add_i32 s35, s35, 1
	s_add_i32 s0, s35, s14
	s_mul_hi_i32 s1, s0, s64
	s_mul_i32 s0, s0, s64
	s_add_u32 s0, s0, s46
	s_addc_u32 s1, s1, s16
	s_mov_b32 s100, 0
	s_cmp_lg_u32 s64, 0x100
	s_cbranch_scc1 .Lq_nosplit
	s_cmp_lg_u32 s1, 0
	s_cbranch_scc1 .Lq_nosplit
	s_and_b32 s98, s56, 0xffffff00
	s_sub_u32 s99, s56, s98
	s_cmp_eq_u32 s99, 0
	s_cbranch_scc1 .Lq_nosplit
	s_cmp_gt_u32 s99, 0x40
	s_cbranch_scc1 .Lq_nosplit
	s_cmp_lt_u32 s0, s98
	s_cbranch_scc1 .Lq_nosplit
	s_sub_u32 s99, s0, s98
	s_and_b32 s100, s99, 3
	s_add_u32 s100, s100, 1
	s_lshr_b32 s99, s99, 2
	s_add_u32 s0, s98, s99
	s_cmp_lt_u32 s0, s56
	s_cselect_b32 s100, s100, 0

;     DI bool next(int i, Unit& u) const { const int L = (i0 + i) * G + c - start; if (L >= 144) return false; const int bt = L >> 2; u.pm = L & 3; u.pn = (bt / 9) * 16 + (bt % 9); u.kob = 256 * u.pm; return true; }
; template <class Epi, class SchedT>
; DI void gemm_phase(LAS unsigned char* lds, const Gemm g, const SchedT& S, const Epi& E) {
;     ...
;     for (;;) {
;         const bool has_next = S.next(ui + 1, nxt);
;         const char* nA = has_next ? (const char*)g.A + (size_t)nxt.pm * tstepA : cA; const char* nB = has_next ? (const char*)g.Bt + (size_t)nxt.pn * tstepB + (size_t)nxt.kob * 2 : cB;
;         for (int t = 0; t < nt; t += 2) {
;             const bool last = (t == nt - 2);
;             const char* a1 = cA + (size_t)(t + 1) * kstep;
;             const char* a2 = last ? nA : cA + (size_t)(t + 2) * kstep; const char* b2 = last ? nB : cB + (size_t)(t + 2) * kstep;
;             const char* a3 = a2 + kstep; const char* b3 = b2 + kstep;
;     ...
; #pragma unroll
;         for (int a = 0; a < 2; ++a)
; #pragma unroll
;             for (int b = 0; b < 2; ++b)
; #pragma unroll
;                 for (int m = 0; m < 4; ++m)
; #pragma unroll
;                     for (int n = 0; n < 2; ++n) acc[a][b][m][n] = (f32x4){0.f, 0.f, 0.f, 0.f};
;         cur = nxt; cA = nA; cB = nB; ++ui;
.LBB0_1704:
	s_cmp_eq_u32 s100, 0
	s_cbranch_scc1 .Lq_noofs
	s_sub_u32 s98, s100, 1
	s_mul_i32 s98, s98, 0xb00
	s_add_u32 s6, s6, s98
	s_addc_u32 s7, s7, 0
	s_add_u32 s0, s0, s98
	s_addc_u32 s1, s1, 0
.Lq_noofs:
	s_add_u32 s8, s8, 0x160080
	s_addc_u32 s9, s9, 0
	s_add_u32 s39, s10, 0x100
	v_mov_b32_e32 v2, 0
	v_mov_b32_e32 v35, v1
	s_addc_u32 s40, s11, 0
	s_mov_b32 s41, -2
	s_cmp_eq_u32 s32, 0
	s_cbranch_scc1 .Lq_fullk
	s_mov_b32 s41, 64
.Lq_fullk:
	v_mov_b32_e32 v3, v2
	v_mov_b32_e32 v4, v2
	v_mov_b32_e32 v5, v2
	v_mov_b32_e32 v6, v2
	v_mov_b32_e32 v7, v2
	v_mov_b32_e32 v8, v2
	v_mov_b32_e32 v9, v2
	v_mov_b32_e32 v18, v2
	v_mov_b32_e32 v19, v2
	s_waitcnt vmcnt(0)
	v_mov_b32_e32 v20, v2
	v_mov_b32_e32 v21, v2
	v_mov_b32_e32 v22, v2
	v_mov_b32_e32 v23, v2
	v_mov_b32_e32 v24, v2
	v_mov_b32_e32 v25, v2
	v_mov_b32_e32 v38, v2
	v_mov_b32_e32 v39, v2
	v_mov_b32_e32 v40, v2
	v_mov_b32_e32 v41, v2
	v_mov_b32_e32 v42, v2
	v_mov_b32_e32 v43, v2
	v_mov_b32_e32 v44, v2
	v_mov_b32_e32 v45, v2
	v_mov_b32_e32 v66, v2
	v_mov_b32_e32 v67, v2
	v_mov_b32_e32 v68, v2
	v_mov_b32_e32 v69, v2
	v_mov_b32_e32 v70, v2
	v_mov_b32_e32 v71, v2
	v_mov_b32_e32 v72, v2
	v_mov_b32_e32 v73, v2
	v_mov_b32_e32 v10, v2
	v_mov_b32_e32 v11, v2
	v_mov_b32_e32 v12, v2
	v_mov_b32_e32 v13, v2
	v_mov_b32_e32 v14, v2
	v_mov_b32_e32 v15, v2
	v_mov_b32_e32 v16, v2
	v_mov_b32_e32 v17, v2
	v_mov_b32_e32 v26, v2
	v_mov_b32_e32 v27, v2
	v_mov_b32_e32 v28, v2
	v_mov_b32_e32 v29, v2
	v_mov_b32_e32 v30, v2
	v_mov_b32_e32 v31, v2
	v_mov_b32_e32 v32, v2
	v_mov_b32_e32 v33, v2
	v_mov_b32_e32 v50, v2
	v_mov_b32_e32 v51, v2
	v_mov_b32_e32 v52, v2
	v_mov_b32_e32 v53, v2
	v_mov_b32_e32 v58, v2
	v_mov_b32_e32 v59, v2
	v_mov_b32_e32 v60, v2
	v_mov_b32_e32 v61, v2
	v_mov_b32_e32 v74, v2
	v_mov_b32_e32 v75, v2
	v_mov_b32_e32 v76, v2
	v_mov_b32_e32 v77, v2
	v_mov_b32_e32 v78, v2
	v_mov_b32_e32 v79, v2
	v_mov_b32_e32 v80, v2
	v_mov_b32_e32 v81, v2
	v_mov_b32_e32 v82, v2
	v_mov_b32_e32 v83, v2
	v_mov_b32_e32 v84, v2
	v_mov_b32_e32 v85, v2
	v_mov_b32_e32 v86, v2
	v_mov_b32_e32 v87, v2
	v_mov_b32_e32 v88, v2
	v_mov_b32_e32 v89, v2
	v_mov_b32_e32 v98, v2
	v_mov_b32_e32 v99, v2
	v_mov_b32_e32 v100, v2
	v_mov_b32_e32 v101, v2
	v_mov_b32_e32 v102, v2
	v_mov_b32_e32 v103, v2
	v_mov_b32_e32 v104, v2
	v_mov_b32_e32 v105, v2
	v_mov_b32_e32 v114, v2
	v_mov_b32_e32 v115, v2
	v_mov_b32_e32 v116, v2
	v_mov_b32_e32 v117, v2
	v_mov_b32_e32 v118, v2
	v_mov_b32_e32 v119, v2
	v_mov_b32_e32 v120, v2
	v_mov_b32_e32 v121, v2
	v_mov_b32_e32 v130, v2
	v_mov_b32_e32 v131, v2
	v_mov_b32_e32 v132, v2
	v_mov_b32_e32 v133, v2
	v_mov_b32_e32 v134, v2
	v_mov_b32_e32 v135, v2
	v_mov_b32_e32 v136, v2
	v_mov_b32_e32 v137, v2
	v_mov_b32_e32 v90, v2
	v_mov_b32_e32 v91, v2
	v_mov_b32_e32 v92, v2
	v_mov_b32_e32 v93, v2
	v_mov_b32_e32 v94, v2
	v_mov_b32_e32 v95, v2
	v_mov_b32_e32 v96, v2
	v_mov_b32_e32 v97, v2
	v_mov_b32_e32 v106, v2
	v_mov_b32_e32 v107, v2
	v_mov_b32_e32 v108, v2
	v_mov_b32_e32 v109, v2
	v_mov_b32_e32 v110, v2
	v_mov_b32_e32 v111, v2
	v_mov_b32_e32 v112, v2
	v_mov_b32_e32 v113, v2
	v_mov_b32_e32 v122, v2
	v_mov_b32_e32 v123, v2
	v_mov_b32_e32 v124, v2
	v_mov_b32_e32 v125, v2
	v_mov_b32_e32 v126, v2
	v_mov_b32_e32 v127, v2
	v_mov_b32_e32 v128, v2
	v_mov_b32_e32 v129, v2
	v_mov_b32_e32 v138, v2
	v_mov_b32_e32 v139, v2
	v_mov_b32_e32 v140, v2
	v_mov_b32_e32 v141, v2
	v_mov_b32_e32 v142, v2
	v_mov_b32_e32 v143, v2
	v_mov_b32_e32 v144, v2
	v_mov_b32_e32 v145, v2
.LBB0_1705:
	s_add_u32 s10, s8, 0xffea0080
	s_addc_u32 s11, s9, -1
	s_add_i32 s42, 0, 0x10000
	v_add_u32_e32 v36, s42, v150
	ds_read_b128 v[46:49], v36
	ds_read_b128 v[54:57], v36 offset:1024
	ds_read_b128 v[62:65], v36 offset:2048
	ds_read_b128 v[152:155], v36 offset:3072
	s_cmpk_eq_i32 s41, 0x54
	s_cselect_b32 s13, s7, s11
	s_cselect_b32 s12, s6, s10
	s_cselect_b32 s11, s1, s40
	s_cselect_b32 s10, s0, s39
	v_lshl_add_u64 v[36:37], s[8:9], 0, v[0:1]
	s_add_i32 m0, s24, 0xc000
	ds_read_b128 v[156:159], v151
	ds_read_b128 v[160:163], v151 offset:1024
	ds_read_b128 v[164:167], v151 offset:2048
	ds_read_b128 v[168:171], v151 offset:3072
	ds_read_b128 v[172:175], v151 offset:4096
	ds_read_b128 v[176:179], v151 offset:5120
	ds_read_b128 v[184:187], v151 offset:6144
	ds_read_b128 v[188:191], v151 offset:7168
	global_load_lds_dwordx4 v[36:37], off
	v_lshl_add_u64 v[36:37], s[8:9], 0, v[34:35]
	s_add_i32 m0, s24, 0xe000
	s_nop 0
	global_load_lds_dwordx4 v[36:37], off
	s_waitcnt lgkmcnt(8)
	s_barrier
	s_waitcnt lgkmcnt(0)
	s_setprio 1
	s_waitcnt lgkmcnt(0)
	v_mfma_f32_16x16x32_bf16 v[142:145], v[46:49], v[156:159], v[142:145]
	v_mfma_f32_16x16x32_bf16 v[138:141], v[62:65], v[156:159], v[138:141]
	v_mfma_f32_16x16x32_bf16 v[126:129], v[46:49], v[164:167], v[126:129]
	v_mfma_f32_16x16x32_bf16 v[122:125], v[62:65], v[164:167], v[122:125]
	v_mfma_f32_16x16x32_bf16 v[110:113], v[46:49], v[172:175], v[110:113]
	v_mfma_f32_16x16x32_bf16 v[106:109], v[62:65], v[172:175], v[106:109]
	v_mfma_f32_16x16x32_bf16 v[94:97], v[46:49], v[184:187], v[94:97]
	v_mfma_f32_16x16x32_bf16 v[90:93], v[62:65], v[184:187], v[90:93]
	v_mfma_f32_16x16x32_bf16 v[142:145], v[54:57], v[160:163], v[142:145]
	v_mfma_f32_16x16x32_bf16 v[138:141], v[152:155], v[160:163], v[138:141]
	v_mfma_f32_16x16x32_bf16 v[126:129], v[54:57], v[168:171], v[126:129]
	v_mfma_f32_16x16x32_bf16 v[122:125], v[152:155], v[168:171], v[122:125]
	v_mfma_f32_16x16x32_bf16 v[110:113], v[54:57], v[176:179], v[110:113]
	v_mfma_f32_16x16x32_bf16 v[106:109], v[152:155], v[176:179], v[106:109]
	v_mfma_f32_16x16x32_bf16 v[94:97], v[54:57], v[188:191], v[94:97]
	v_mfma_f32_16x16x32_bf16 v[90:93], v[152:155], v[188:191], v[90:93]
	s_setprio 0
	s_barrier
; #define PG8_STAGE(bufoff, gbase, voff) do { _Pragma("unroll") for (int _i = 0; _i < 2; ++_i) \
;         __builtin_amdgcn_global_load_lds((const unsigned*)((const char*)(gbase) + (voff)[_i]), (LAS unsigned*)(lds + (bufoff) + ldsw + _i * 8192), 16, 0, 0); } while (0)
; #define PG8_LDA(dst, b, h) do { _Pragma("unroll") for (int m = 0; m < 4; ++m) _Pragma("unroll") for (int k = 0; k < 2; ++k) dst[m][k] = *(const LAS bf16x8*)(lds + PG8_SA(b, h) + aoff + m * 2048 + k * 1024); } while (0)
; #define PG8_LDB(dst, b, h) do { _Pragma("unroll") for (int n = 0; n < 2; ++n) _Pragma("unroll") for (int k = 0; k < 2; ++k) dst[n][k] = *(const LAS bf16x8*)(lds + PG8_SB(b, h) + boff + n * 2048 + k * 1024); } while (0)
; #define PG8_MMA(ai, bj, At, Bt) do { __builtin_amdgcn_s_setprio(1); _Pragma("unroll") for (int m = 0; m < 4; ++m) _Pragma("unroll") for (int n = 0; n < 2; ++n) _Pragma("unroll") for (int k = 0; k < 2; ++k) \
;         acc[ai][bj][m][n] = __builtin_amdgcn_mfma_f32_16x16x32_bf16(Bt[n][k], At[m][k], acc[ai][bj][m][n], 0, 0, 0); __builtin_amdgcn_s_setprio(0); } while (0)
; #define PG8_WAIT_V(n) asm volatile("s_waitcnt vmcnt(" #n ")" ::: "memory")
; #define PG8_WAIT_L(n) asm volatile("s_waitcnt lgkmcnt(" #n ")" ::: "memory")
; #define PG8_BAR __builtin_amdgcn_s_barrier()
; #define PG8_SCHED __builtin_amdgcn_sched_barrier(0)
; template <class Epi, class SchedT>
; DI void gemm_phase(LAS unsigned char* lds, const Gemm g, const SchedT& S, const Epi& E) {
;     ...
;             PG8_WAIT_L(8); PG8_BAR; PG8_WAIT_L(0); PG8_MMA(0, 0, At, B0); PG8_BAR; PG8_SCHED;
;             PG8_LDB(B1, 0, 1); PG8_STAGE(PG8_SB(0, 0), b2, voffB);
;             PG8_BAR; PG8_WAIT_L(0); PG8_MMA(0, 1, At, B1); PG8_BAR;
;             PG8_LDA(At, 0, 1); PG8_STAGE(PG8_SA(0, 0), a2, voffA);
;             PG8_BAR; PG8_WAIT_L(0); PG8_MMA(1, 0, At, B0); PG8_BAR; PG8_SCHED;
;             PG8_STAGE(PG8_SB(0, 1), b2 + hstepB, voffB);
;             PG8_WAIT_V(6); PG8_BAR; PG8_MMA(1, 1, At, B1); PG8_BAR;
;             PG8_LDB(B0, 1, 0); PG8_SCHED; PG8_LDA(At, 1, 0); PG8_STAGE(PG8_SA(0, 1), a2 + hstepA, voffA);
;             PG8_WAIT_L(8); PG8_BAR; PG8_WAIT_L(0); PG8_MMA(0, 0, At, B0); PG8_BAR; PG8_SCHED;
	s_add_i32 s44, 0, 0x14000
	s_add_i32 s42, s42, s18
	v_add_u32_e32 v36, s44, v150
	v_lshl_add_u64 v[146:147], s[10:11], 0, v[0:1]
	s_mov_b32 m0, s42
	ds_read_b128 v[202:205], v36
	ds_read_b128 v[206:209], v36 offset:1024
	ds_read_b128 v[210:213], v36 offset:2048
	ds_read_b128 v[214:217], v36 offset:3072
	global_load_lds_dwordx4 v[146:147], off
	v_lshl_add_u64 v[180:181], s[10:11], 0, v[34:35]
	s_add_i32 m0, s42, 0x2000
	s_nop 0
	global_load_lds_dwordx4 v[180:181], off
	s_barrier
	s_waitcnt lgkmcnt(0)
	s_setprio 1
	s_waitcnt lgkmcnt(0)
	v_mfma_f32_16x16x32_bf16 v[134:137], v[202:205], v[156:159], v[134:137]
	v_mfma_f32_16x16x32_bf16 v[130:133], v[210:213], v[156:159], v[130:133]
	v_mfma_f32_16x16x32_bf16 v[118:121], v[202:205], v[164:167], v[118:121]
	v_mfma_f32_16x16x32_bf16 v[114:117], v[210:213], v[164:167], v[114:117]
	v_mfma_f32_16x16x32_bf16 v[102:105], v[202:205], v[172:175], v[102:105]
	v_mfma_f32_16x16x32_bf16 v[98:101], v[210:213], v[172:175], v[98:101]
	v_mfma_f32_16x16x32_bf16 v[86:89], v[202:205], v[184:187], v[86:89]
	v_mfma_f32_16x16x32_bf16 v[82:85], v[210:213], v[184:187], v[82:85]
	v_mfma_f32_16x16x32_bf16 v[134:137], v[206:209], v[160:163], v[134:137]
	v_mfma_f32_16x16x32_bf16 v[130:133], v[214:217], v[160:163], v[130:133]
	v_mfma_f32_16x16x32_bf16 v[118:121], v[206:209], v[168:171], v[118:121]
	v_mfma_f32_16x16x32_bf16 v[114:117], v[214:217], v[168:171], v[114:117]
	v_mfma_f32_16x16x32_bf16 v[102:105], v[206:209], v[176:179], v[102:105]
	v_mfma_f32_16x16x32_bf16 v[98:101], v[214:217], v[176:179], v[98:101]
	v_mfma_f32_16x16x32_bf16 v[86:89], v[206:209], v[188:191], v[86:89]
	v_mfma_f32_16x16x32_bf16 v[82:85], v[214:217], v[188:191], v[82:85]
	s_setprio 0
	s_mov_b32 m0, s24
	v_lshl_add_u64 v[182:183], s[12:13], 0, v[0:1]
	s_barrier
	ds_read_b128 v[156:159], v151 offset:16384
	ds_read_b128 v[160:163], v151 offset:17408
	ds_read_b128 v[164:167], v151 offset:18432
	ds_read_b128 v[168:171], v151 offset:19456
	ds_read_b128 v[172:175], v151 offset:20480
	ds_read_b128 v[176:179], v151 offset:21504
	ds_read_b128 v[184:187], v151 offset:22528
	ds_read_b128 v[188:191], v151 offset:23552
	global_load_lds_dwordx4 v[182:183], off
	v_lshl_add_u64 v[194:195], s[12:13], 0, v[34:35]
	s_mov_b32 m0, s25
	s_nop 0
	global_load_lds_dwordx4 v[194:195], off
	s_barrier
	s_waitcnt lgkmcnt(0)
	s_setprio 1
	s_waitcnt lgkmcnt(0)
	v_mfma_f32_16x16x32_bf16 v[78:81], v[46:49], v[156:159], v[78:81]
	v_mfma_f32_16x16x32_bf16 v[74:77], v[62:65], v[156:159], v[74:77]
	v_mfma_f32_16x16x32_bf16 v[58:61], v[46:49], v[164:167], v[58:61]
	v_mfma_f32_16x16x32_bf16 v[50:53], v[62:65], v[164:167], v[50:53]
	v_mfma_f32_16x16x32_bf16 v[30:33], v[46:49], v[172:175], v[30:33]
	v_mfma_f32_16x16x32_bf16 v[26:29], v[62:65], v[172:175], v[26:29]
	v_mfma_f32_16x16x32_bf16 v[14:17], v[46:49], v[184:187], v[14:17]
	v_mfma_f32_16x16x32_bf16 v[10:13], v[62:65], v[184:187], v[10:13]
	v_mfma_f32_16x16x32_bf16 v[78:81], v[54:57], v[160:163], v[78:81]
	v_mfma_f32_16x16x32_bf16 v[74:77], v[152:155], v[160:163], v[74:77]
	v_mfma_f32_16x16x32_bf16 v[58:61], v[54:57], v[168:171], v[58:61]
	v_mfma_f32_16x16x32_bf16 v[50:53], v[152:155], v[168:171], v[50:53]
	v_mfma_f32_16x16x32_bf16 v[30:33], v[54:57], v[176:179], v[30:33]
	v_mfma_f32_16x16x32_bf16 v[26:29], v[152:155], v[176:179], v[26:29]
	v_mfma_f32_16x16x32_bf16 v[14:17], v[54:57], v[188:191], v[14:17]
	v_mfma_f32_16x16x32_bf16 v[10:13], v[152:155], v[188:191], v[10:13]
	s_setprio 0
	s_barrier
	s_add_u32 s42, s10, 0x160000
	s_addc_u32 s43, s11, 0
	s_add_i32 s44, s44, s18
	v_lshl_add_u64 v[36:37], s[42:43], 0, v[0:1]
	s_mov_b32 m0, s44
	s_nop 0
	global_load_lds_dwordx4 v[36:37], off
	v_lshl_add_u64 v[36:37], s[42:43], 0, v[34:35]
	s_add_i32 m0, s44, 0x2000
	s_nop 0
	global_load_lds_dwordx4 v[36:37], off
	s_waitcnt vmcnt(6)
	s_barrier
	s_setprio 1
	v_mfma_f32_16x16x32_bf16 v[42:45], v[202:205], v[164:167], v[42:45]
	v_mfma_f32_16x16x32_bf16 v[36:39], v[210:213], v[164:167], v[38:41]
	v_mfma_f32_16x16x32_bf16 v[22:25], v[202:205], v[172:175], v[22:25]
	v_mfma_f32_16x16x32_bf16 v[18:21], v[210:213], v[172:175], v[18:21]
	v_mfma_f32_16x16x32_bf16 v[6:9], v[202:205], v[184:187], v[6:9]
	v_mfma_f32_16x16x32_bf16 v[2:5], v[210:213], v[184:187], v[2:5]
	v_mfma_f32_16x16x32_bf16 v[46:49], v[202:205], v[156:159], v[70:73]
	v_mfma_f32_16x16x32_bf16 v[54:57], v[210:213], v[156:159], v[66:69]
	v_mfma_f32_16x16x32_bf16 v[42:45], v[206:209], v[168:171], v[42:45]
	v_mfma_f32_16x16x32_bf16 v[36:39], v[214:217], v[168:171], v[36:39]
	v_mfma_f32_16x16x32_bf16 v[22:25], v[206:209], v[176:179], v[22:25]
	v_mfma_f32_16x16x32_bf16 v[18:21], v[214:217], v[176:179], v[18:21]
	v_mfma_f32_16x16x32_bf16 v[6:9], v[206:209], v[188:191], v[6:9]
	v_mfma_f32_16x16x32_bf16 v[2:5], v[214:217], v[188:191], v[2:5]
	v_mfma_f32_16x16x32_bf16 v[46:49], v[206:209], v[160:163], v[46:49]
	v_mfma_f32_16x16x32_bf16 v[54:57], v[214:217], v[160:163], v[54:57]
	s_setprio 0
	s_add_i32 s42, 0, 0x18000
	v_add_u32_e32 v40, s42, v150
	s_barrier
	ds_read_b128 v[62:65], v40
	ds_read_b128 v[66:69], v40 offset:1024
	ds_read_b128 v[70:73], v40 offset:2048
	ds_read_b128 v[152:155], v40 offset:3072
	s_add_u32 s12, s12, 0x160000
	s_addc_u32 s13, s13, 0
	s_mov_b32 m0, s26
	v_lshl_add_u64 v[40:41], s[12:13], 0, v[0:1]
	ds_read_b128 v[156:159], v151 offset:32768
	ds_read_b128 v[160:163], v151 offset:33792
	ds_read_b128 v[164:167], v151 offset:34816
	ds_read_b128 v[168:171], v151 offset:35840
	ds_read_b128 v[172:175], v151 offset:36864
	ds_read_b128 v[176:179], v151 offset:37888
	ds_read_b128 v[184:187], v151 offset:38912
	ds_read_b128 v[188:191], v151 offset:39936
	global_load_lds_dwordx4 v[40:41], off
	v_lshl_add_u64 v[40:41], s[12:13], 0, v[34:35]
	s_mov_b32 m0, s27
	s_nop 0
	global_load_lds_dwordx4 v[40:41], off
	s_waitcnt lgkmcnt(8)
	s_barrier
; #define PG8_STAGE(bufoff, gbase, voff) do { _Pragma("unroll") for (int _i = 0; _i < 2; ++_i) \
;         __builtin_amdgcn_global_load_lds((const unsigned*)((const char*)(gbase) + (voff)[_i]), (LAS unsigned*)(lds + (bufoff) + ldsw + _i * 8192), 16, 0, 0); } while (0)
; #define PG8_LDA(dst, b, h) do { _Pragma("unroll") for (int m = 0; m < 4; ++m) _Pragma("unroll") for (int k = 0; k < 2; ++k) dst[m][k] = *(const LAS bf16x8*)(lds + PG8_SA(b, h) + aoff + m * 2048 + k * 1024); } while (0)
; #define PG8_LDB(dst, b, h) do { _Pragma("unroll") for (int n = 0; n < 2; ++n) _Pragma("unroll") for (int k = 0; k < 2; ++k) dst[n][k] = *(const LAS bf16x8*)(lds + PG8_SB(b, h) + boff + n * 2048 + k * 1024); } while (0)
; #define PG8_MMA(ai, bj, At, Bt) do { __builtin_amdgcn_s_setprio(1); _Pragma("unroll") for (int m = 0; m < 4; ++m) _Pragma("unroll") for (int n = 0; n < 2; ++n) _Pragma("unroll") for (int k = 0; k < 2; ++k) \
;         acc[ai][bj][m][n] = __builtin_amdgcn_mfma_f32_16x16x32_bf16(Bt[n][k], At[m][k], acc[ai][bj][m][n], 0, 0, 0); __builtin_amdgcn_s_setprio(0); } while (0)
; #define PG8_WAIT_L(n) asm volatile("s_waitcnt lgkmcnt(" #n ")" ::: "memory")
; #define PG8_BAR __builtin_amdgcn_s_barrier()
; #define PG8_SCHED __builtin_amdgcn_sched_barrier(0)
; template <class Epi, class SchedT>
; DI void gemm_phase(LAS unsigned char* lds, const Gemm g, const SchedT& S, const Epi& E) {
;     ...
;             PG8_WAIT_L(8); PG8_BAR; PG8_WAIT_L(0); PG8_MMA(0, 0, At, B0); PG8_BAR; PG8_SCHED;
;             PG8_LDB(B1, 1, 1); PG8_STAGE(PG8_SB(1, 0), b3, voffB);
;             PG8_BAR; PG8_WAIT_L(0); PG8_MMA(0, 1, At, B1); PG8_BAR;
;             PG8_LDA(At, 1, 1); PG8_STAGE(PG8_SA(1, 0), a3, voffA);
;             PG8_BAR; PG8_WAIT_L(0); PG8_MMA(1, 0, At, B0); PG8_BAR; PG8_SCHED;
	s_waitcnt lgkmcnt(0)
	s_setprio 1
	s_waitcnt lgkmcnt(0)
	v_mfma_f32_16x16x32_bf16 v[142:145], v[62:65], v[156:159], v[142:145]
	v_mfma_f32_16x16x32_bf16 v[138:141], v[70:73], v[156:159], v[138:141]
	v_mfma_f32_16x16x32_bf16 v[126:129], v[62:65], v[164:167], v[126:129]
	v_mfma_f32_16x16x32_bf16 v[122:125], v[70:73], v[164:167], v[122:125]
	v_mfma_f32_16x16x32_bf16 v[110:113], v[62:65], v[172:175], v[110:113]
	v_mfma_f32_16x16x32_bf16 v[106:109], v[70:73], v[172:175], v[106:109]
	v_mfma_f32_16x16x32_bf16 v[94:97], v[62:65], v[184:187], v[94:97]
	v_mfma_f32_16x16x32_bf16 v[90:93], v[70:73], v[184:187], v[90:93]
	v_mfma_f32_16x16x32_bf16 v[142:145], v[66:69], v[160:163], v[142:145]
	v_mfma_f32_16x16x32_bf16 v[138:141], v[152:155], v[160:163], v[138:141]
	v_mfma_f32_16x16x32_bf16 v[126:129], v[66:69], v[168:171], v[126:129]
	v_mfma_f32_16x16x32_bf16 v[122:125], v[152:155], v[168:171], v[122:125]
	v_mfma_f32_16x16x32_bf16 v[110:113], v[66:69], v[176:179], v[110:113]
	v_mfma_f32_16x16x32_bf16 v[106:109], v[152:155], v[176:179], v[106:109]
	v_mfma_f32_16x16x32_bf16 v[94:97], v[66:69], v[188:191], v[94:97]
	v_mfma_f32_16x16x32_bf16 v[90:93], v[152:155], v[188:191], v[90:93]
	s_setprio 0
	s_barrier
	s_add_i32 s12, 0, 0x1c000
	v_add_u32_e32 v40, s12, v150
	s_add_i32 s13, s42, s18
	ds_read_b128 v[202:205], v40
	ds_read_b128 v[206:209], v40 offset:1024
	ds_read_b128 v[210:213], v40 offset:2048
	ds_read_b128 v[214:217], v40 offset:3072
	v_lshl_add_u64 v[40:41], v[146:147], 0, s[90:91]
	s_mov_b32 m0, s13
	s_nop 0
	global_load_lds_dwordx4 v[40:41], off
	v_lshl_add_u64 v[40:41], v[180:181], 0, s[90:91]
	s_add_i32 m0, s13, 0x2000
	s_nop 0
	global_load_lds_dwordx4 v[40:41], off
	s_barrier
	s_waitcnt lgkmcnt(0)
	s_setprio 1
	s_waitcnt lgkmcnt(0)
	v_mfma_f32_16x16x32_bf16 v[134:137], v[202:205], v[156:159], v[134:137]
	v_mfma_f32_16x16x32_bf16 v[130:133], v[210:213], v[156:159], v[130:133]
	v_mfma_f32_16x16x32_bf16 v[118:121], v[202:205], v[164:167], v[118:121]
	v_mfma_f32_16x16x32_bf16 v[114:117], v[210:213], v[164:167], v[114:117]
	v_mfma_f32_16x16x32_bf16 v[102:105], v[202:205], v[172:175], v[102:105]
	v_mfma_f32_16x16x32_bf16 v[98:101], v[210:213], v[172:175], v[98:101]
	v_mfma_f32_16x16x32_bf16 v[86:89], v[202:205], v[184:187], v[86:89]
	v_mfma_f32_16x16x32_bf16 v[82:85], v[210:213], v[184:187], v[82:85]
	v_mfma_f32_16x16x32_bf16 v[134:137], v[206:209], v[160:163], v[134:137]
	v_mfma_f32_16x16x32_bf16 v[130:133], v[214:217], v[160:163], v[130:133]
	v_mfma_f32_16x16x32_bf16 v[118:121], v[206:209], v[168:171], v[118:121]
	v_mfma_f32_16x16x32_bf16 v[114:117], v[214:217], v[168:171], v[114:117]
	v_mfma_f32_16x16x32_bf16 v[102:105], v[206:209], v[176:179], v[102:105]
	v_mfma_f32_16x16x32_bf16 v[98:101], v[214:217], v[176:179], v[98:101]
	v_mfma_f32_16x16x32_bf16 v[86:89], v[206:209], v[188:191], v[86:89]
	v_mfma_f32_16x16x32_bf16 v[82:85], v[214:217], v[188:191], v[82:85]
	s_setprio 0
	s_mov_b32 m0, s31
	v_lshl_add_u64 v[40:41], v[182:183], 0, s[90:91]
	s_barrier
	ds_read_b128 v[156:159], v151 offset:49152
	ds_read_b128 v[160:163], v151 offset:50176
	ds_read_b128 v[164:167], v151 offset:51200
	ds_read_b128 v[168:171], v151 offset:52224
	ds_read_b128 v[172:175], v151 offset:53248
	ds_read_b128 v[176:179], v151 offset:54272
	ds_read_b128 v[184:187], v151 offset:55296
	ds_read_b128 v[188:191], v151 offset:56320
	global_load_lds_dwordx4 v[40:41], off
	v_lshl_add_u64 v[40:41], v[194:195], 0, s[90:91]
	s_mov_b32 m0, s34
	s_nop 0
	global_load_lds_dwordx4 v[40:41], off
	s_barrier
	s_waitcnt lgkmcnt(0)
	s_setprio 1
	s_waitcnt lgkmcnt(0)
	v_mfma_f32_16x16x32_bf16 v[78:81], v[62:65], v[156:159], v[78:81]
	v_mfma_f32_16x16x32_bf16 v[74:77], v[70:73], v[156:159], v[74:77]
	v_mfma_f32_16x16x32_bf16 v[58:61], v[62:65], v[164:167], v[58:61]
	v_mfma_f32_16x16x32_bf16 v[50:53], v[70:73], v[164:167], v[50:53]
	v_mfma_f32_16x16x32_bf16 v[30:33], v[62:65], v[172:175], v[30:33]
	v_mfma_f32_16x16x32_bf16 v[26:29], v[70:73], v[172:175], v[26:29]
	v_mfma_f32_16x16x32_bf16 v[14:17], v[62:65], v[184:187], v[14:17]
	v_mfma_f32_16x16x32_bf16 v[10:13], v[70:73], v[184:187], v[10:13]
	v_mfma_f32_16x16x32_bf16 v[78:81], v[66:69], v[160:163], v[78:81]
	v_mfma_f32_16x16x32_bf16 v[74:77], v[152:155], v[160:163], v[74:77]
	v_mfma_f32_16x16x32_bf16 v[58:61], v[66:69], v[168:171], v[58:61]
	v_mfma_f32_16x16x32_bf16 v[50:53], v[152:155], v[168:171], v[50:53]
	v_mfma_f32_16x16x32_bf16 v[30:33], v[66:69], v[176:179], v[30:33]
	v_mfma_f32_16x16x32_bf16 v[26:29], v[152:155], v[176:179], v[26:29]
	v_mfma_f32_16x16x32_bf16 v[14:17], v[66:69], v[188:191], v[14:17]
	v_mfma_f32_16x16x32_bf16 v[10:13], v[152:155], v[188:191], v[10:13]
	s_setprio 0
	s_barrier
	s_add_u32 s10, s10, 0x160080
	s_addc_u32 s11, s11, 0
	s_add_i32 s12, s12, s18
	v_lshl_add_u64 v[40:41], s[10:11], 0, v[0:1]
	s_mov_b32 m0, s12
	s_nop 0
	global_load_lds_dwordx4 v[40:41], off
	v_lshl_add_u64 v[40:41], s[10:11], 0, v[34:35]
	s_add_i32 m0, s12, 0x2000
	s_nop 0
	global_load_lds_dwordx4 v[40:41], off
	s_waitcnt vmcnt(6)
	s_barrier
; #define PG8_MMA(ai, bj, At, Bt) do { __builtin_amdgcn_s_setprio(1); _Pragma("unroll") for (int m = 0; m < 4; ++m) _Pragma("unroll") for (int n = 0; n < 2; ++n) _Pragma("unroll") for (int k = 0; k < 2; ++k) \
;         acc[ai][bj][m][n] = __builtin_amdgcn_mfma_f32_16x16x32_bf16(Bt[n][k], At[m][k], acc[ai][bj][m][n], 0, 0, 0); __builtin_amdgcn_s_setprio(0); } while (0)
; #define PG8_WAIT_V(n) asm volatile("s_waitcnt vmcnt(" #n ")" ::: "memory")
; #define PG8_BAR __builtin_amdgcn_s_barrier()
; template <class Epi, class SchedT>
; DI void gemm_phase(LAS unsigned char* lds, const Gemm g, const SchedT& S, const Epi& E) {
;     ...
;             PG8_WAIT_V(6); PG8_BAR; PG8_MMA(1, 1, At, B1); PG8_BAR;
;         }
;         { int fr2 = fr, fq2 = fq, wr2 = wr, wc2 = wc; asm volatile("" : "+v"(fr2), "+v"(fq2), "+s"(wr2), "+s"(wc2));
;           E(acc, cur, wr2, wc2, fr2, fq2); }
	s_setprio 1
	v_mfma_f32_16x16x32_bf16 v[46:49], v[202:205], v[156:159], v[46:49]
	v_mfma_f32_16x16x32_bf16 v[70:73], v[206:209], v[160:163], v[46:49]
	v_mfma_f32_16x16x32_bf16 v[46:49], v[210:213], v[156:159], v[54:57]
	v_mfma_f32_16x16x32_bf16 v[40:43], v[202:205], v[164:167], v[42:45]
	v_mfma_f32_16x16x32_bf16 v[36:39], v[210:213], v[164:167], v[36:39]
	v_mfma_f32_16x16x32_bf16 v[22:25], v[202:205], v[172:175], v[22:25]
	v_mfma_f32_16x16x32_bf16 v[18:21], v[210:213], v[172:175], v[18:21]
	v_mfma_f32_16x16x32_bf16 v[6:9], v[202:205], v[184:187], v[6:9]
	v_mfma_f32_16x16x32_bf16 v[2:5], v[210:213], v[184:187], v[2:5]
	v_mfma_f32_16x16x32_bf16 v[66:69], v[214:217], v[160:163], v[46:49]
	v_mfma_f32_16x16x32_bf16 v[42:45], v[206:209], v[168:171], v[40:43]
	v_mfma_f32_16x16x32_bf16 v[38:41], v[214:217], v[168:171], v[36:39]
	v_mfma_f32_16x16x32_bf16 v[22:25], v[206:209], v[176:179], v[22:25]
	v_mfma_f32_16x16x32_bf16 v[18:21], v[214:217], v[176:179], v[18:21]
	v_mfma_f32_16x16x32_bf16 v[6:9], v[206:209], v[188:191], v[6:9]
	v_mfma_f32_16x16x32_bf16 v[2:5], v[214:217], v[188:191], v[2:5]
	s_setprio 0
	s_add_i32 s41, s41, 2
	s_add_u32 s8, s8, 0x100
	s_addc_u32 s9, s9, 0
	s_add_u32 s39, s39, 0x100
	s_addc_u32 s40, s40, 0
	s_cmpk_gt_u32 s41, 0x55
	s_barrier
	s_cbranch_scc0 .LBB0_1705
	s_cmp_eq_u32 s32, 0
	s_cbranch_scc1 .Lq_epi_normal
	s_sub_u32 s12, s38, 64
	s_lshl_b32 s13, s33, 2
	s_add_u32 s12, s12, s13
	s_lshl_b32 s101, s12, 2
	s_sub_u32 s98, s32, 1
	s_add_u32 s13, s101, s98
	s_lshl_b32 s13, s13, 18
	s_add_u32 s8, s4, 0xcd01000
	s_addc_u32 s9, s5, 0
	s_add_u32 s8, s8, s13
	s_addc_u32 s9, s9, 0
	s_lshl_b32 s13, s12, 2
	s_sub_u32 s10, s4, 0x800
	s_subb_u32 s11, s5, 0
	s_add_u32 s10, s10, s13
	s_addc_u32 s11, s11, 0
	v_lshlrev_b32_e32 v202, 3, v192
	global_store_dwordx2 v202, v[144:145], s[8:9]
	s_add_u32 s8, s8, 0x1000
	s_addc_u32 s9, s9, 0
	global_store_dwordx2 v202, v[142:143], s[8:9]
	s_add_u32 s8, s8, 0x1000
	s_addc_u32 s9, s9, 0
	global_store_dwordx2 v202, v[140:141], s[8:9]
	s_add_u32 s8, s8, 0x1000
	s_addc_u32 s9, s9, 0
	global_store_dwordx2 v202, v[138:139], s[8:9]
	s_add_u32 s8, s8, 0x1000
	s_addc_u32 s9, s9, 0
	global_store_dwordx2 v202, v[136:137], s[8:9]
	s_add_u32 s8, s8, 0x1000
	s_addc_u32 s9, s9, 0
	global_store_dwordx2 v202, v[134:135], s[8:9]
	s_add_u32 s8, s8, 0x1000
	s_addc_u32 s9, s9, 0
	global_store_dwordx2 v202, v[132:133], s[8:9]
	s_add_u32 s8, s8, 0x1000
	s_addc_u32 s9, s9, 0
	global_store_dwordx2 v202, v[130:131], s[8:9]
	s_add_u32 s8, s8, 0x1000
	s_addc_u32 s9, s9, 0
	global_store_dwordx2 v202, v[128:129], s[8:9]
	s_add_u32 s8, s8, 0x1000
	s_addc_u32 s9, s9, 0
	global_store_dwordx2 v202, v[126:127], s[8:9]
	s_add_u32 s8, s8, 0x1000
	s_addc_u32 s9, s9, 0
	global_store_dwordx2 v202, v[124:125], s[8:9]
	s_add_u32 s8, s8, 0x1000
	s_addc_u32 s9, s9, 0
	global_store_dwordx2 v202, v[122:123], s[8:9]
	s_add_u32 s8, s8, 0x1000
	s_addc_u32 s9, s9, 0
	global_store_dwordx2 v202, v[120:121], s[8:9]
	s_add_u32 s8, s8, 0x1000
	s_addc_u32 s9, s9, 0
	global_store_dwordx2 v202, v[118:119], s[8:9]
	s_add_u32 s8, s8, 0x1000
	s_addc_u32 s9, s9, 0
	global_store_dwordx2 v202, v[116:117], s[8:9]
	s_add_u32 s8, s8, 0x1000
	s_addc_u32 s9, s9, 0
	global_store_dwordx2 v202, v[114:115], s[8:9]
	s_add_u32 s8, s8, 0x1000
	s_addc_u32 s9, s9, 0
	global_store_dwordx2 v202, v[112:113], s[8:9]
	s_add_u32 s8, s8, 0x1000
	s_addc_u32 s9, s9, 0
	global_store_dwordx2 v202, v[110:111], s[8:9]
	s_add_u32 s8, s8, 0x1000
	s_addc_u32 s9, s9, 0
	global_store_dwordx2 v202, v[108:109], s[8:9]
	s_add_u32 s8, s8, 0x1000
	s_addc_u32 s9, s9, 0
	global_store_dwordx2 v202, v[106:107], s[8:9]
	s_add_u32 s8, s8, 0x1000
	s_addc_u32 s9, s9, 0
	global_store_dwordx2 v202, v[104:105], s[8:9]
	s_add_u32 s8, s8, 0x1000
	s_addc_u32 s9, s9, 0
	global_store_dwordx2 v202, v[102:103], s[8:9]
	s_add_u32 s8, s8, 0x1000
	s_addc_u32 s9, s9, 0
	global_store_dwordx2 v202, v[100:101], s[8:9]
	s_add_u32 s8, s8, 0x1000
	s_addc_u32 s9, s9, 0
	global_store_dwordx2 v202, v[98:99], s[8:9]
	s_add_u32 s8, s8, 0x1000
	s_addc_u32 s9, s9, 0
	global_store_dwordx2 v202, v[96:97], s[8:9]
	s_add_u32 s8, s8, 0x1000
	s_addc_u32 s9, s9, 0
	global_store_dwordx2 v202, v[94:95], s[8:9]
	s_add_u32 s8, s8, 0x1000
	s_addc_u32 s9, s9, 0
	global_store_dwordx2 v202, v[92:93], s[8:9]
	s_add_u32 s8, s8, 0x1000
	s_addc_u32 s9, s9, 0
	global_store_dwordx2 v202, v[90:91], s[8:9]
	s_add_u32 s8, s8, 0x1000
	s_addc_u32 s9, s9, 0
	global_store_dwordx2 v202, v[88:89], s[8:9]
	s_add_u32 s8, s8, 0x1000
	s_addc_u32 s9, s9, 0
	global_store_dwordx2 v202, v[86:87], s[8:9]
	s_add_u32 s8, s8, 0x1000
	s_addc_u32 s9, s9, 0
	global_store_dwordx2 v202, v[84:85], s[8:9]
	s_add_u32 s8, s8, 0x1000
	s_addc_u32 s9, s9, 0
	global_store_dwordx2 v202, v[82:83], s[8:9]
	s_add_u32 s8, s8, 0x1000
	s_addc_u32 s9, s9, 0
	global_store_dwordx2 v202, v[80:81], s[8:9]
	s_add_u32 s8, s8, 0x1000
	s_addc_u32 s9, s9, 0
	global_store_dwordx2 v202, v[78:79], s[8:9]
	s_add_u32 s8, s8, 0x1000
	s_addc_u32 s9, s9, 0
	global_store_dwordx2 v202, v[76:77], s[8:9]
	s_add_u32 s8, s8, 0x1000
	s_addc_u32 s9, s9, 0
	global_store_dwordx2 v202, v[74:75], s[8:9]
	s_add_u32 s8, s8, 0x1000
	s_addc_u32 s9, s9, 0
	global_store_dwordx2 v202, v[72:73], s[8:9]
	s_add_u32 s8, s8, 0x1000
	s_addc_u32 s9, s9, 0
	global_store_dwordx2 v202, v[70:71], s[8:9]
	s_add_u32 s8, s8, 0x1000
	s_addc_u32 s9, s9, 0
	global_store_dwordx2 v202, v[68:69], s[8:9]
	s_add_u32 s8, s8, 0x1000
	s_addc_u32 s9, s9, 0
	global_store_dwordx2 v202, v[66:67], s[8:9]
	s_add_u32 s8, s8, 0x1000
	s_addc_u32 s9, s9, 0
	global_store_dwordx2 v202, v[60:61], s[8:9]
	s_add_u32 s8, s8, 0x1000
	s_addc_u32 s9, s9, 0
; template <class Epi, class SchedT>
; DI void gemm_phase(LAS unsigned char* lds, const Gemm g, const SchedT& S, const Epi& E) {
;     ...
;         { int fr2 = fr, fq2 = fq, wr2 = wr, wc2 = wc; asm volatile("" : "+v"(fr2), "+v"(fq2), "+s"(wr2), "+s"(wc2));
;           E(acc, cur, wr2, wc2, fr2, fq2); }
	global_store_dwordx2 v202, v[58:59], s[8:9]
	s_add_u32 s8, s8, 0x1000
	s_addc_u32 s9, s9, 0
	global_store_dwordx2 v202, v[52:53], s[8:9]
	s_add_u32 s8, s8, 0x1000
	s_addc_u32 s9, s9, 0
	global_store_dwordx2 v202, v[50:51], s[8:9]
	s_add_u32 s8, s8, 0x1000
	s_addc_u32 s9, s9, 0
	global_store_dwordx2 v202, v[44:45], s[8:9]
	s_add_u32 s8, s8, 0x1000
	s_addc_u32 s9, s9, 0
	global_store_dwordx2 v202, v[42:43], s[8:9]
	s_add_u32 s8, s8, 0x1000
	s_addc_u32 s9, s9, 0
	global_store_dwordx2 v202, v[40:41], s[8:9]
	s_add_u32 s8, s8, 0x1000
	s_addc_u32 s9, s9, 0
	global_store_dwordx2 v202, v[38:39], s[8:9]
	s_add_u32 s8, s8, 0x1000
	s_addc_u32 s9, s9, 0
	global_store_dwordx2 v202, v[32:33], s[8:9]
	s_add_u32 s8, s8, 0x1000
	s_addc_u32 s9, s9, 0
	global_store_dwordx2 v202, v[30:31], s[8:9]
	s_add_u32 s8, s8, 0x1000
	s_addc_u32 s9, s9, 0
	global_store_dwordx2 v202, v[28:29], s[8:9]
	s_add_u32 s8, s8, 0x1000
	s_addc_u32 s9, s9, 0
	global_store_dwordx2 v202, v[26:27], s[8:9]
	s_add_u32 s8, s8, 0x1000
	s_addc_u32 s9, s9, 0
	global_store_dwordx2 v202, v[24:25], s[8:9]
	s_add_u32 s8, s8, 0x1000
	s_addc_u32 s9, s9, 0
	global_store_dwordx2 v202, v[22:23], s[8:9]
	s_add_u32 s8, s8, 0x1000
	s_addc_u32 s9, s9, 0
	global_store_dwordx2 v202, v[20:21], s[8:9]
	s_add_u32 s8, s8, 0x1000
	s_addc_u32 s9, s9, 0
	global_store_dwordx2 v202, v[18:19], s[8:9]
	s_add_u32 s8, s8, 0x1000
	s_addc_u32 s9, s9, 0
	global_store_dwordx2 v202, v[16:17], s[8:9]
	s_add_u32 s8, s8, 0x1000
	s_addc_u32 s9, s9, 0
	global_store_dwordx2 v202, v[14:15], s[8:9]
	s_add_u32 s8, s8, 0x1000
	s_addc_u32 s9, s9, 0
	global_store_dwordx2 v202, v[12:13], s[8:9]
	s_add_u32 s8, s8, 0x1000
	s_addc_u32 s9, s9, 0
	global_store_dwordx2 v202, v[10:11], s[8:9]
	s_add_u32 s8, s8, 0x1000
	s_addc_u32 s9, s9, 0
	global_store_dwordx2 v202, v[8:9], s[8:9]
	s_add_u32 s8, s8, 0x1000
	s_addc_u32 s9, s9, 0
	global_store_dwordx2 v202, v[6:7], s[8:9]
	s_add_u32 s8, s8, 0x1000
	s_addc_u32 s9, s9, 0
	global_store_dwordx2 v202, v[4:5], s[8:9]
	s_add_u32 s8, s8, 0x1000
	s_addc_u32 s9, s9, 0
	global_store_dwordx2 v202, v[2:3], s[8:9]
	s_add_u32 s8, s8, 0x1000
	s_addc_u32 s9, s9, 0
	s_waitcnt vmcnt(0)
	s_barrier
	v_cmp_eq_u32_e32 vcc, 0, v192
	s_and_saveexec_b64 s[98:99], vcc
	s_cbranch_execz .Lq_t0done
	buffer_wbl2 sc1
	s_waitcnt vmcnt(0)
	v_mov_b32_e32 v203, 1
	v_mov_b32_e32 v204, 0
	global_atomic_add v203, v204, v203, s[10:11] sc0
	s_waitcnt vmcnt(0)
	buffer_inv sc1
	s_waitcnt vmcnt(0)
	v_mov_b32_e32 v204, 0x20400
	ds_write_b32 v204, v203
	s_waitcnt lgkmcnt(0)
.Lq_t0done:
	s_or_b64 exec, exec, s[98:99]
	s_barrier
	v_mov_b32_e32 v204, 0x20400
	ds_read_b32 v203, v204
	s_waitcnt lgkmcnt(0)
	v_readfirstlane_b32 s12, v203
	s_nop 3
	s_cmp_eq_u32 s12, 3
	s_cbranch_scc1 .Lq_last
	s_mov_b64 s[8:9], -1
	s_and_b64 vcc, exec, s[2:3]
	s_branch .Lq_epi_end
.Lq_last:
	s_lshl_b32 s13, s101, 18
	s_add_u32 s8, s4, 0xcd01000
	s_addc_u32 s9, s5, 0
	s_add_u32 s8, s8, s13
	s_addc_u32 s9, s9, 0
	global_load_dwordx2 v[144:145], v202, s[8:9]
	s_add_u32 s8, s8, 0x1000
	s_addc_u32 s9, s9, 0
	global_load_dwordx2 v[142:143], v202, s[8:9]
	s_add_u32 s8, s8, 0x1000
	s_addc_u32 s9, s9, 0
	global_load_dwordx2 v[140:141], v202, s[8:9]
	s_add_u32 s8, s8, 0x1000
	s_addc_u32 s9, s9, 0
	global_load_dwordx2 v[138:139], v202, s[8:9]
	s_add_u32 s8, s8, 0x1000
	s_addc_u32 s9, s9, 0
	global_load_dwordx2 v[136:137], v202, s[8:9]
	s_add_u32 s8, s8, 0x1000
	s_addc_u32 s9, s9, 0
	global_load_dwordx2 v[134:135], v202, s[8:9]
	s_add_u32 s8, s8, 0x1000
	s_addc_u32 s9, s9, 0
	global_load_dwordx2 v[132:133], v202, s[8:9]
	s_add_u32 s8, s8, 0x1000
	s_addc_u32 s9, s9, 0
	global_load_dwordx2 v[130:131], v202, s[8:9]
	s_add_u32 s8, s8, 0x1000
	s_addc_u32 s9, s9, 0
	global_load_dwordx2 v[128:129], v202, s[8:9]
	s_add_u32 s8, s8, 0x1000
	s_addc_u32 s9, s9, 0
	global_load_dwordx2 v[126:127], v202, s[8:9]
	s_add_u32 s8, s8, 0x1000
	s_addc_u32 s9, s9, 0
	global_load_dwordx2 v[124:125], v202, s[8:9]
	s_add_u32 s8, s8, 0x1000
	s_addc_u32 s9, s9, 0
	global_load_dwordx2 v[122:123], v202, s[8:9]
	s_add_u32 s8, s8, 0x1000
	s_addc_u32 s9, s9, 0
	global_load_dwordx2 v[120:121], v202, s[8:9]
	s_add_u32 s8, s8, 0x1000
	s_addc_u32 s9, s9, 0
	global_load_dwordx2 v[118:119], v202, s[8:9]
	s_add_u32 s8, s8, 0x1000
	s_addc_u32 s9, s9, 0
	global_load_dwordx2 v[116:117], v202, s[8:9]
	s_add_u32 s8, s8, 0x1000
	s_addc_u32 s9, s9, 0
	global_load_dwordx2 v[114:115], v202, s[8:9]
	s_add_u32 s8, s8, 0x1000
	s_addc_u32 s9, s9, 0
	global_load_dwordx2 v[112:113], v202, s[8:9]
	s_add_u32 s8, s8, 0x1000
	s_addc_u32 s9, s9, 0
	global_load_dwordx2 v[110:111], v202, s[8:9]
	s_add_u32 s8, s8, 0x1000
	s_addc_u32 s9, s9, 0
	global_load_dwordx2 v[108:109], v202, s[8:9]
	s_add_u32 s8, s8, 0x1000
	s_addc_u32 s9, s9, 0
	global_load_dwordx2 v[106:107], v202, s[8:9]
	s_add_u32 s8, s8, 0x1000
	s_addc_u32 s9, s9, 0
	global_load_dwordx2 v[104:105], v202, s[8:9]
	s_add_u32 s8, s8, 0x1000
	s_addc_u32 s9, s9, 0
	global_load_dwordx2 v[102:103], v202, s[8:9]
	s_add_u32 s8, s8, 0x1000
	s_addc_u32 s9, s9, 0
	global_load_dwordx2 v[100:101], v202, s[8:9]
	s_add_u32 s8, s8, 0x1000
	s_addc_u32 s9, s9, 0
	global_load_dwordx2 v[98:99], v202, s[8:9]
	s_add_u32 s8, s8, 0x1000
	s_addc_u32 s9, s9, 0
	global_load_dwordx2 v[96:97], v202, s[8:9]
	s_add_u32 s8, s8, 0x1000
	s_addc_u32 s9, s9, 0
	global_load_dwordx2 v[94:95], v202, s[8:9]
	s_add_u32 s8, s8, 0x1000
	s_addc_u32 s9, s9, 0
	global_load_dwordx2 v[92:93], v202, s[8:9]
	s_add_u32 s8, s8, 0x1000
	s_addc_u32 s9, s9, 0
	global_load_dwordx2 v[90:91], v202, s[8:9]
	s_add_u32 s8, s8, 0x1000
	s_addc_u32 s9, s9, 0
	global_load_dwordx2 v[88:89], v202, s[8:9]
	s_add_u32 s8, s8, 0x1000
; template <class Epi, class SchedT>
; DI void gemm_phase(LAS unsigned char* lds, const Gemm g, const SchedT& S, const Epi& E) {
;     ...
;         { int fr2 = fr, fq2 = fq, wr2 = wr, wc2 = wc; asm volatile("" : "+v"(fr2), "+v"(fq2), "+s"(wr2), "+s"(wc2));
;           E(acc, cur, wr2, wc2, fr2, fq2); }
	s_addc_u32 s9, s9, 0
	global_load_dwordx2 v[86:87], v202, s[8:9]
	s_add_u32 s8, s8, 0x1000
	s_addc_u32 s9, s9, 0
	global_load_dwordx2 v[84:85], v202, s[8:9]
	s_add_u32 s8, s8, 0x1000
	s_addc_u32 s9, s9, 0
	global_load_dwordx2 v[82:83], v202, s[8:9]
	s_add_u32 s8, s8, 0x1000
	s_addc_u32 s9, s9, 0
	global_load_dwordx2 v[80:81], v202, s[8:9]
	s_add_u32 s8, s8, 0x1000
	s_addc_u32 s9, s9, 0
	global_load_dwordx2 v[78:79], v202, s[8:9]
	s_add_u32 s8, s8, 0x1000
	s_addc_u32 s9, s9, 0
	global_load_dwordx2 v[76:77], v202, s[8:9]
	s_add_u32 s8, s8, 0x1000
	s_addc_u32 s9, s9, 0
	global_load_dwordx2 v[74:75], v202, s[8:9]
	s_add_u32 s8, s8, 0x1000
	s_addc_u32 s9, s9, 0
	global_load_dwordx2 v[72:73], v202, s[8:9]
	s_add_u32 s8, s8, 0x1000
	s_addc_u32 s9, s9, 0
	global_load_dwordx2 v[70:71], v202, s[8:9]
	s_add_u32 s8, s8, 0x1000
	s_addc_u32 s9, s9, 0
	global_load_dwordx2 v[68:69], v202, s[8:9]
	s_add_u32 s8, s8, 0x1000
	s_addc_u32 s9, s9, 0
	global_load_dwordx2 v[66:67], v202, s[8:9]
	s_add_u32 s8, s8, 0x1000
	s_addc_u32 s9, s9, 0
	global_load_dwordx2 v[60:61], v202, s[8:9]
	s_add_u32 s8, s8, 0x1000
	s_addc_u32 s9, s9, 0
	global_load_dwordx2 v[58:59], v202, s[8:9]
	s_add_u32 s8, s8, 0x1000
	s_addc_u32 s9, s9, 0
	global_load_dwordx2 v[52:53], v202, s[8:9]
	s_add_u32 s8, s8, 0x1000
	s_addc_u32 s9, s9, 0
	global_load_dwordx2 v[50:51], v202, s[8:9]
	s_add_u32 s8, s8, 0x1000
	s_addc_u32 s9, s9, 0
	global_load_dwordx2 v[44:45], v202, s[8:9]
	s_add_u32 s8, s8, 0x1000
	s_addc_u32 s9, s9, 0
	global_load_dwordx2 v[42:43], v202, s[8:9]
	s_add_u32 s8, s8, 0x1000
	s_addc_u32 s9, s9, 0
	global_load_dwordx2 v[40:41], v202, s[8:9]
	s_add_u32 s8, s8, 0x1000
	s_addc_u32 s9, s9, 0
	global_load_dwordx2 v[38:39], v202, s[8:9]
	s_add_u32 s8, s8, 0x1000
	s_addc_u32 s9, s9, 0
	global_load_dwordx2 v[32:33], v202, s[8:9]
	s_add_u32 s8, s8, 0x1000
	s_addc_u32 s9, s9, 0
	global_load_dwordx2 v[30:31], v202, s[8:9]
	s_add_u32 s8, s8, 0x1000
	s_addc_u32 s9, s9, 0
	global_load_dwordx2 v[28:29], v202, s[8:9]
	s_add_u32 s8, s8, 0x1000
	s_addc_u32 s9, s9, 0
	global_load_dwordx2 v[26:27], v202, s[8:9]
	s_add_u32 s8, s8, 0x1000
	s_addc_u32 s9, s9, 0
	global_load_dwordx2 v[24:25], v202, s[8:9]
	s_add_u32 s8, s8, 0x1000
	s_addc_u32 s9, s9, 0
	global_load_dwordx2 v[22:23], v202, s[8:9]
	s_add_u32 s8, s8, 0x1000
	s_addc_u32 s9, s9, 0
	global_load_dwordx2 v[20:21], v202, s[8:9]
	s_add_u32 s8, s8, 0x1000
	s_addc_u32 s9, s9, 0
	global_load_dwordx2 v[18:19], v202, s[8:9]
	s_add_u32 s8, s8, 0x1000
	s_addc_u32 s9, s9, 0
	global_load_dwordx2 v[16:17], v202, s[8:9]
	s_add_u32 s8, s8, 0x1000
	s_addc_u32 s9, s9, 0
	global_load_dwordx2 v[14:15], v202, s[8:9]
	s_add_u32 s8, s8, 0x1000
	s_addc_u32 s9, s9, 0
	global_load_dwordx2 v[12:13], v202, s[8:9]
	s_add_u32 s8, s8, 0x1000
	s_addc_u32 s9, s9, 0
	global_load_dwordx2 v[10:11], v202, s[8:9]
	s_add_u32 s8, s8, 0x1000
	s_addc_u32 s9, s9, 0
	global_load_dwordx2 v[8:9], v202, s[8:9]
	s_add_u32 s8, s8, 0x1000
	s_addc_u32 s9, s9, 0
	global_load_dwordx2 v[6:7], v202, s[8:9]
	s_add_u32 s8, s8, 0x1000
	s_addc_u32 s9, s9, 0
	global_load_dwordx2 v[4:5], v202, s[8:9]
	s_add_u32 s8, s8, 0x1000
	s_addc_u32 s9, s9, 0
	global_load_dwordx2 v[2:3], v202, s[8:9]
	s_add_u32 s8, s8, 0x1000
	s_addc_u32 s9, s9, 0
	s_waitcnt vmcnt(0)
	global_load_dwordx2 v[156:157], v202, s[8:9]
	s_add_u32 s8, s8, 0x1000
	s_addc_u32 s9, s9, 0
	global_load_dwordx2 v[158:159], v202, s[8:9]
	s_add_u32 s8, s8, 0x1000
	s_addc_u32 s9, s9, 0
	global_load_dwordx2 v[160:161], v202, s[8:9]
	s_add_u32 s8, s8, 0x1000
	s_addc_u32 s9, s9, 0
	global_load_dwordx2 v[162:163], v202, s[8:9]
	s_add_u32 s8, s8, 0x1000
	s_addc_u32 s9, s9, 0
	global_load_dwordx2 v[164:165], v202, s[8:9]
	s_add_u32 s8, s8, 0x1000
	s_addc_u32 s9, s9, 0
	global_load_dwordx2 v[166:167], v202, s[8:9]
	s_add_u32 s8, s8, 0x1000
	s_addc_u32 s9, s9, 0
	global_load_dwordx2 v[168:169], v202, s[8:9]
	s_add_u32 s8, s8, 0x1000
	s_addc_u32 s9, s9, 0
	global_load_dwordx2 v[170:171], v202, s[8:9]
	s_add_u32 s8, s8, 0x1000
	s_addc_u32 s9, s9, 0
	global_load_dwordx2 v[172:173], v202, s[8:9]
	s_add_u32 s8, s8, 0x1000
	s_addc_u32 s9, s9, 0
	global_load_dwordx2 v[174:175], v202, s[8:9]
	s_add_u32 s8, s8, 0x1000
	s_addc_u32 s9, s9, 0
	global_load_dwordx2 v[176:177], v202, s[8:9]
	s_add_u32 s8, s8, 0x1000
	s_addc_u32 s9, s9, 0
	global_load_dwordx2 v[178:179], v202, s[8:9]
	s_add_u32 s8, s8, 0x1000
	s_addc_u32 s9, s9, 0
	global_load_dwordx2 v[184:185], v202, s[8:9]
	s_add_u32 s8, s8, 0x1000
	s_addc_u32 s9, s9, 0
	global_load_dwordx2 v[186:187], v202, s[8:9]
	s_add_u32 s8, s8, 0x1000
	s_addc_u32 s9, s9, 0
	global_load_dwordx2 v[188:189], v202, s[8:9]
	s_add_u32 s8, s8, 0x1000
	s_addc_u32 s9, s9, 0
	global_load_dwordx2 v[190:191], v202, s[8:9]
	s_add_u32 s8, s8, 0x1000
	s_addc_u32 s9, s9, 0
	s_waitcnt vmcnt(0)
; template <class Epi, class SchedT>
; DI void gemm_phase(LAS unsigned char* lds, const Gemm g, const SchedT& S, const Epi& E) {
;     ...
;         { int fr2 = fr, fq2 = fq, wr2 = wr, wc2 = wc; asm volatile("" : "+v"(fr2), "+v"(fq2), "+s"(wr2), "+s"(wc2));
;           E(acc, cur, wr2, wc2, fr2, fq2); }
	v_pk_add_f32 v[144:145], v[144:145], v[156:157]
	v_pk_add_f32 v[142:143], v[142:143], v[158:159]
	v_pk_add_f32 v[140:141], v[140:141], v[160:161]
	v_pk_add_f32 v[138:139], v[138:139], v[162:163]
	v_pk_add_f32 v[136:137], v[136:137], v[164:165]
	v_pk_add_f32 v[134:135], v[134:135], v[166:167]
	v_pk_add_f32 v[132:133], v[132:133], v[168:169]
	v_pk_add_f32 v[130:131], v[130:131], v[170:171]
	v_pk_add_f32 v[128:129], v[128:129], v[172:173]
	v_pk_add_f32 v[126:127], v[126:127], v[174:175]
	v_pk_add_f32 v[124:125], v[124:125], v[176:177]
	v_pk_add_f32 v[122:123], v[122:123], v[178:179]
	v_pk_add_f32 v[120:121], v[120:121], v[184:185]
	v_pk_add_f32 v[118:119], v[118:119], v[186:187]
	v_pk_add_f32 v[116:117], v[116:117], v[188:189]
	v_pk_add_f32 v[114:115], v[114:115], v[190:191]
	global_load_dwordx2 v[156:157], v202, s[8:9]
	s_add_u32 s8, s8, 0x1000
	s_addc_u32 s9, s9, 0
	global_load_dwordx2 v[158:159], v202, s[8:9]
	s_add_u32 s8, s8, 0x1000
	s_addc_u32 s9, s9, 0
	global_load_dwordx2 v[160:161], v202, s[8:9]
	s_add_u32 s8, s8, 0x1000
	s_addc_u32 s9, s9, 0
	global_load_dwordx2 v[162:163], v202, s[8:9]
	s_add_u32 s8, s8, 0x1000
	s_addc_u32 s9, s9, 0
	global_load_dwordx2 v[164:165], v202, s[8:9]
	s_add_u32 s8, s8, 0x1000
	s_addc_u32 s9, s9, 0
	global_load_dwordx2 v[166:167], v202, s[8:9]
	s_add_u32 s8, s8, 0x1000
	s_addc_u32 s9, s9, 0
	global_load_dwordx2 v[168:169], v202, s[8:9]
	s_add_u32 s8, s8, 0x1000
	s_addc_u32 s9, s9, 0
	global_load_dwordx2 v[170:171], v202, s[8:9]
	s_add_u32 s8, s8, 0x1000
	s_addc_u32 s9, s9, 0
	global_load_dwordx2 v[172:173], v202, s[8:9]
	s_add_u32 s8, s8, 0x1000
	s_addc_u32 s9, s9, 0
	global_load_dwordx2 v[174:175], v202, s[8:9]
	s_add_u32 s8, s8, 0x1000
	s_addc_u32 s9, s9, 0
	global_load_dwordx2 v[176:177], v202, s[8:9]
	s_add_u32 s8, s8, 0x1000
	s_addc_u32 s9, s9, 0
	global_load_dwordx2 v[178:179], v202, s[8:9]
	s_add_u32 s8, s8, 0x1000
	s_addc_u32 s9, s9, 0
	global_load_dwordx2 v[184:185], v202, s[8:9]
	s_add_u32 s8, s8, 0x1000
	s_addc_u32 s9, s9, 0
	global_load_dwordx2 v[186:187], v202, s[8:9]
	s_add_u32 s8, s8, 0x1000
	s_addc_u32 s9, s9, 0
	global_load_dwordx2 v[188:189], v202, s[8:9]
	s_add_u32 s8, s8, 0x1000
	s_addc_u32 s9, s9, 0
	global_load_dwordx2 v[190:191], v202, s[8:9]
	s_add_u32 s8, s8, 0x1000
	s_addc_u32 s9, s9, 0
	s_waitcnt vmcnt(0)
	v_pk_add_f32 v[112:113], v[112:113], v[156:157]
	v_pk_add_f32 v[110:111], v[110:111], v[158:159]
	v_pk_add_f32 v[108:109], v[108:109], v[160:161]
	v_pk_add_f32 v[106:107], v[106:107], v[162:163]
	v_pk_add_f32 v[104:105], v[104:105], v[164:165]
	v_pk_add_f32 v[102:103], v[102:103], v[166:167]
	v_pk_add_f32 v[100:101], v[100:101], v[168:169]
	v_pk_add_f32 v[98:99], v[98:99], v[170:171]
	v_pk_add_f32 v[96:97], v[96:97], v[172:173]
	v_pk_add_f32 v[94:95], v[94:95], v[174:175]
	v_pk_add_f32 v[92:93], v[92:93], v[176:177]
	v_pk_add_f32 v[90:91], v[90:91], v[178:179]
	v_pk_add_f32 v[88:89], v[88:89], v[184:185]
	v_pk_add_f32 v[86:87], v[86:87], v[186:187]
	v_pk_add_f32 v[84:85], v[84:85], v[188:189]
	v_pk_add_f32 v[82:83], v[82:83], v[190:191]
	global_load_dwordx2 v[156:157], v202, s[8:9]
	s_add_u32 s8, s8, 0x1000
	s_addc_u32 s9, s9, 0
	global_load_dwordx2 v[158:159], v202, s[8:9]
	s_add_u32 s8, s8, 0x1000
	s_addc_u32 s9, s9, 0
	global_load_dwordx2 v[160:161], v202, s[8:9]
	s_add_u32 s8, s8, 0x1000
	s_addc_u32 s9, s9, 0
	global_load_dwordx2 v[162:163], v202, s[8:9]
	s_add_u32 s8, s8, 0x1000
	s_addc_u32 s9, s9, 0
	global_load_dwordx2 v[164:165], v202, s[8:9]
	s_add_u32 s8, s8, 0x1000
	s_addc_u32 s9, s9, 0
	global_load_dwordx2 v[166:167], v202, s[8:9]
	s_add_u32 s8, s8, 0x1000
	s_addc_u32 s9, s9, 0
	global_load_dwordx2 v[168:169], v202, s[8:9]
	s_add_u32 s8, s8, 0x1000
	s_addc_u32 s9, s9, 0
	global_load_dwordx2 v[170:171], v202, s[8:9]
	s_add_u32 s8, s8, 0x1000
	s_addc_u32 s9, s9, 0
	global_load_dwordx2 v[172:173], v202, s[8:9]
	s_add_u32 s8, s8, 0x1000
	s_addc_u32 s9, s9, 0
	global_load_dwordx2 v[174:175], v202, s[8:9]
	s_add_u32 s8, s8, 0x1000
	s_addc_u32 s9, s9, 0
	global_load_dwordx2 v[176:177], v202, s[8:9]
	s_add_u32 s8, s8, 0x1000
	s_addc_u32 s9, s9, 0
	global_load_dwordx2 v[178:179], v202, s[8:9]
	s_add_u32 s8, s8, 0x1000
	s_addc_u32 s9, s9, 0
	global_load_dwordx2 v[184:185], v202, s[8:9]
	s_add_u32 s8, s8, 0x1000
	s_addc_u32 s9, s9, 0
	global_load_dwordx2 v[186:187], v202, s[8:9]
	s_add_u32 s8, s8, 0x1000
	s_addc_u32 s9, s9, 0
	global_load_dwordx2 v[188:189], v202, s[8:9]
	s_add_u32 s8, s8, 0x1000
	s_addc_u32 s9, s9, 0
	global_load_dwordx2 v[190:191], v202, s[8:9]
	s_add_u32 s8, s8, 0x1000
	s_addc_u32 s9, s9, 0
	s_waitcnt vmcnt(0)
; template <class Epi, class SchedT>
; DI void gemm_phase(LAS unsigned char* lds, const Gemm g, const SchedT& S, const Epi& E) {
;     ...
;         { int fr2 = fr, fq2 = fq, wr2 = wr, wc2 = wc; asm volatile("" : "+v"(fr2), "+v"(fq2), "+s"(wr2), "+s"(wc2));
;           E(acc, cur, wr2, wc2, fr2, fq2); }
	v_pk_add_f32 v[80:81], v[80:81], v[156:157]
	v_pk_add_f32 v[78:79], v[78:79], v[158:159]
	v_pk_add_f32 v[76:77], v[76:77], v[160:161]
	v_pk_add_f32 v[74:75], v[74:75], v[162:163]
	v_pk_add_f32 v[72:73], v[72:73], v[164:165]
	v_pk_add_f32 v[70:71], v[70:71], v[166:167]
	v_pk_add_f32 v[68:69], v[68:69], v[168:169]
	v_pk_add_f32 v[66:67], v[66:67], v[170:171]
	v_pk_add_f32 v[60:61], v[60:61], v[172:173]
	v_pk_add_f32 v[58:59], v[58:59], v[174:175]
	v_pk_add_f32 v[52:53], v[52:53], v[176:177]
	v_pk_add_f32 v[50:51], v[50:51], v[178:179]
	v_pk_add_f32 v[44:45], v[44:45], v[184:185]
	v_pk_add_f32 v[42:43], v[42:43], v[186:187]
	v_pk_add_f32 v[40:41], v[40:41], v[188:189]
	v_pk_add_f32 v[38:39], v[38:39], v[190:191]
	global_load_dwordx2 v[156:157], v202, s[8:9]
	s_add_u32 s8, s8, 0x1000
	s_addc_u32 s9, s9, 0
	global_load_dwordx2 v[158:159], v202, s[8:9]
	s_add_u32 s8, s8, 0x1000
	s_addc_u32 s9, s9, 0
	global_load_dwordx2 v[160:161], v202, s[8:9]
	s_add_u32 s8, s8, 0x1000
	s_addc_u32 s9, s9, 0
	global_load_dwordx2 v[162:163], v202, s[8:9]
	s_add_u32 s8, s8, 0x1000
	s_addc_u32 s9, s9, 0
	global_load_dwordx2 v[164:165], v202, s[8:9]
	s_add_u32 s8, s8, 0x1000
	s_addc_u32 s9, s9, 0
	global_load_dwordx2 v[166:167], v202, s[8:9]
	s_add_u32 s8, s8, 0x1000
	s_addc_u32 s9, s9, 0
	global_load_dwordx2 v[168:169], v202, s[8:9]
	s_add_u32 s8, s8, 0x1000
	s_addc_u32 s9, s9, 0
	global_load_dwordx2 v[170:171], v202, s[8:9]
	s_add_u32 s8, s8, 0x1000
	s_addc_u32 s9, s9, 0
	global_load_dwordx2 v[172:173], v202, s[8:9]
	s_add_u32 s8, s8, 0x1000
	s_addc_u32 s9, s9, 0
	global_load_dwordx2 v[174:175], v202, s[8:9]
	s_add_u32 s8, s8, 0x1000
	s_addc_u32 s9, s9, 0
	global_load_dwordx2 v[176:177], v202, s[8:9]
	s_add_u32 s8, s8, 0x1000
	s_addc_u32 s9, s9, 0
	global_load_dwordx2 v[178:179], v202, s[8:9]
	s_add_u32 s8, s8, 0x1000
	s_addc_u32 s9, s9, 0
	global_load_dwordx2 v[184:185], v202, s[8:9]
	s_add_u32 s8, s8, 0x1000
	s_addc_u32 s9, s9, 0
	global_load_dwordx2 v[186:187], v202, s[8:9]
	s_add_u32 s8, s8, 0x1000
	s_addc_u32 s9, s9, 0
	global_load_dwordx2 v[188:189], v202, s[8:9]
	s_add_u32 s8, s8, 0x1000
	s_addc_u32 s9, s9, 0
	global_load_dwordx2 v[190:191], v202, s[8:9]
	s_add_u32 s8, s8, 0x1000
	s_addc_u32 s9, s9, 0
	s_waitcnt vmcnt(0)
	v_pk_add_f32 v[32:33], v[32:33], v[156:157]
	v_pk_add_f32 v[30:31], v[30:31], v[158:159]
	v_pk_add_f32 v[28:29], v[28:29], v[160:161]
	v_pk_add_f32 v[26:27], v[26:27], v[162:163]
	v_pk_add_f32 v[24:25], v[24:25], v[164:165]
	v_pk_add_f32 v[22:23], v[22:23], v[166:167]
	v_pk_add_f32 v[20:21], v[20:21], v[168:169]
	v_pk_add_f32 v[18:19], v[18:19], v[170:171]
	v_pk_add_f32 v[16:17], v[16:17], v[172:173]
	v_pk_add_f32 v[14:15], v[14:15], v[174:175]
	v_pk_add_f32 v[12:13], v[12:13], v[176:177]
	v_pk_add_f32 v[10:11], v[10:11], v[178:179]
	v_pk_add_f32 v[8:9], v[8:9], v[184:185]
	v_pk_add_f32 v[6:7], v[6:7], v[186:187]
	v_pk_add_f32 v[4:5], v[4:5], v[188:189]
	v_pk_add_f32 v[2:3], v[2:3], v[190:191]
	global_load_dwordx2 v[156:157], v202, s[8:9]
	s_add_u32 s8, s8, 0x1000
	s_addc_u32 s9, s9, 0
	global_load_dwordx2 v[158:159], v202, s[8:9]
	s_add_u32 s8, s8, 0x1000
	s_addc_u32 s9, s9, 0
	global_load_dwordx2 v[160:161], v202, s[8:9]
	s_add_u32 s8, s8, 0x1000
	s_addc_u32 s9, s9, 0
	global_load_dwordx2 v[162:163], v202, s[8:9]
	s_add_u32 s8, s8, 0x1000
	s_addc_u32 s9, s9, 0
	global_load_dwordx2 v[164:165], v202, s[8:9]
	s_add_u32 s8, s8, 0x1000
	s_addc_u32 s9, s9, 0
	global_load_dwordx2 v[166:167], v202, s[8:9]
	s_add_u32 s8, s8, 0x1000
	s_addc_u32 s9, s9, 0
	global_load_dwordx2 v[168:169], v202, s[8:9]
	s_add_u32 s8, s8, 0x1000
	s_addc_u32 s9, s9, 0
	global_load_dwordx2 v[170:171], v202, s[8:9]
	s_add_u32 s8, s8, 0x1000
	s_addc_u32 s9, s9, 0
	global_load_dwordx2 v[172:173], v202, s[8:9]
	s_add_u32 s8, s8, 0x1000
	s_addc_u32 s9, s9, 0
	global_load_dwordx2 v[174:175], v202, s[8:9]
	s_add_u32 s8, s8, 0x1000
	s_addc_u32 s9, s9, 0
	global_load_dwordx2 v[176:177], v202, s[8:9]
	s_add_u32 s8, s8, 0x1000
	s_addc_u32 s9, s9, 0
	global_load_dwordx2 v[178:179], v202, s[8:9]
	s_add_u32 s8, s8, 0x1000
	s_addc_u32 s9, s9, 0
	global_load_dwordx2 v[184:185], v202, s[8:9]
	s_add_u32 s8, s8, 0x1000
	s_addc_u32 s9, s9, 0
	global_load_dwordx2 v[186:187], v202, s[8:9]
	s_add_u32 s8, s8, 0x1000
	s_addc_u32 s9, s9, 0
	global_load_dwordx2 v[188:189], v202, s[8:9]
	s_add_u32 s8, s8, 0x1000
	s_addc_u32 s9, s9, 0
	global_load_dwordx2 v[190:191], v202, s[8:9]
	s_add_u32 s8, s8, 0x1000
	s_addc_u32 s9, s9, 0
	s_waitcnt vmcnt(0)
	v_pk_add_f32 v[144:145], v[144:145], v[156:157]
	v_pk_add_f32 v[142:143], v[142:143], v[158:159]
	v_pk_add_f32 v[140:141], v[140:141], v[160:161]
	v_pk_add_f32 v[138:139], v[138:139], v[162:163]
	v_pk_add_f32 v[136:137], v[136:137], v[164:165]
	v_pk_add_f32 v[134:135], v[134:135], v[166:167]
	v_pk_add_f32 v[132:133], v[132:133], v[168:169]
	v_pk_add_f32 v[130:131], v[130:131], v[170:171]
	v_pk_add_f32 v[128:129], v[128:129], v[172:173]
	v_pk_add_f32 v[126:127], v[126:127], v[174:175]
	v_pk_add_f32 v[124:125], v[124:125], v[176:177]
	v_pk_add_f32 v[122:123], v[122:123], v[178:179]
	v_pk_add_f32 v[120:121], v[120:121], v[184:185]
	v_pk_add_f32 v[118:119], v[118:119], v[186:187]
	v_pk_add_f32 v[116:117], v[116:117], v[188:189]
	v_pk_add_f32 v[114:115], v[114:115], v[190:191]
	global_load_dwordx2 v[156:157], v202, s[8:9]
	s_add_u32 s8, s8, 0x1000
	s_addc_u32 s9, s9, 0
	global_load_dwordx2 v[158:159], v202, s[8:9]
	s_add_u32 s8, s8, 0x1000
	s_addc_u32 s9, s9, 0
	global_load_dwordx2 v[160:161], v202, s[8:9]
	s_add_u32 s8, s8, 0x1000
	s_addc_u32 s9, s9, 0
	global_load_dwordx2 v[162:163], v202, s[8:9]
	s_add_u32 s8, s8, 0x1000
	s_addc_u32 s9, s9, 0
	global_load_dwordx2 v[164:165], v202, s[8:9]
	s_add_u32 s8, s8, 0x1000
	s_addc_u32 s9, s9, 0
	global_load_dwordx2 v[166:167], v202, s[8:9]
	s_add_u32 s8, s8, 0x1000
	s_addc_u32 s9, s9, 0
	global_load_dwordx2 v[168:169], v202, s[8:9]
	s_add_u32 s8, s8, 0x1000
	s_addc_u32 s9, s9, 0
	global_load_dwordx2 v[170:171], v202, s[8:9]
	s_add_u32 s8, s8, 0x1000
	s_addc_u32 s9, s9, 0
	global_load_dwordx2 v[172:173], v202, s[8:9]
	s_add_u32 s8, s8, 0x1000
	s_addc_u32 s9, s9, 0
	global_load_dwordx2 v[174:175], v202, s[8:9]
	s_add_u32 s8, s8, 0x1000
	s_addc_u32 s9, s9, 0
	global_load_dwordx2 v[176:177], v202, s[8:9]
	s_add_u32 s8, s8, 0x1000
	s_addc_u32 s9, s9, 0
	global_load_dwordx2 v[178:179], v202, s[8:9]
	s_add_u32 s8, s8, 0x1000
	s_addc_u32 s9, s9, 0
	global_load_dwordx2 v[184:185], v202, s[8:9]
	s_add_u32 s8, s8, 0x1000
	s_addc_u32 s9, s9, 0
	global_load_dwordx2 v[186:187], v202, s[8:9]
	s_add_u32 s8, s8, 0x1000
	s_addc_u32 s9, s9, 0
	global_load_dwordx2 v[188:189], v202, s[8:9]
	s_add_u32 s8, s8, 0x1000
	s_addc_u32 s9, s9, 0
	global_load_dwordx2 v[190:191], v202, s[8:9]
	s_add_u32 s8, s8, 0x1000
	s_addc_u32 s9, s9, 0
	s_waitcnt vmcnt(0)
; template <class Epi, class SchedT>
; DI void gemm_phase(LAS unsigned char* lds, const Gemm g, const SchedT& S, const Epi& E) {
;     ...
;         { int fr2 = fr, fq2 = fq, wr2 = wr, wc2 = wc; asm volatile("" : "+v"(fr2), "+v"(fq2), "+s"(wr2), "+s"(wc2));
;           E(acc, cur, wr2, wc2, fr2, fq2); }
	v_pk_add_f32 v[112:113], v[112:113], v[156:157]
	v_pk_add_f32 v[110:111], v[110:111], v[158:159]
	v_pk_add_f32 v[108:109], v[108:109], v[160:161]
	v_pk_add_f32 v[106:107], v[106:107], v[162:163]
	v_pk_add_f32 v[104:105], v[104:105], v[164:165]
	v_pk_add_f32 v[102:103], v[102:103], v[166:167]
	v_pk_add_f32 v[100:101], v[100:101], v[168:169]
	v_pk_add_f32 v[98:99], v[98:99], v[170:171]
	v_pk_add_f32 v[96:97], v[96:97], v[172:173]
	v_pk_add_f32 v[94:95], v[94:95], v[174:175]
	v_pk_add_f32 v[92:93], v[92:93], v[176:177]
	v_pk_add_f32 v[90:91], v[90:91], v[178:179]
	v_pk_add_f32 v[88:89], v[88:89], v[184:185]
	v_pk_add_f32 v[86:87], v[86:87], v[186:187]
	v_pk_add_f32 v[84:85], v[84:85], v[188:189]
	v_pk_add_f32 v[82:83], v[82:83], v[190:191]
	global_load_dwordx2 v[156:157], v202, s[8:9]
	s_add_u32 s8, s8, 0x1000
	s_addc_u32 s9, s9, 0
	global_load_dwordx2 v[158:159], v202, s[8:9]
	s_add_u32 s8, s8, 0x1000
	s_addc_u32 s9, s9, 0
	global_load_dwordx2 v[160:161], v202, s[8:9]
	s_add_u32 s8, s8, 0x1000
	s_addc_u32 s9, s9, 0
	global_load_dwordx2 v[162:163], v202, s[8:9]
	s_add_u32 s8, s8, 0x1000
	s_addc_u32 s9, s9, 0
	global_load_dwordx2 v[164:165], v202, s[8:9]
	s_add_u32 s8, s8, 0x1000
	s_addc_u32 s9, s9, 0
	global_load_dwordx2 v[166:167], v202, s[8:9]
	s_add_u32 s8, s8, 0x1000
	s_addc_u32 s9, s9, 0
	global_load_dwordx2 v[168:169], v202, s[8:9]
	s_add_u32 s8, s8, 0x1000
	s_addc_u32 s9, s9, 0
	global_load_dwordx2 v[170:171], v202, s[8:9]
	s_add_u32 s8, s8, 0x1000
	s_addc_u32 s9, s9, 0
	global_load_dwordx2 v[172:173], v202, s[8:9]
	s_add_u32 s8, s8, 0x1000
	s_addc_u32 s9, s9, 0
	global_load_dwordx2 v[174:175], v202, s[8:9]
	s_add_u32 s8, s8, 0x1000
	s_addc_u32 s9, s9, 0
	global_load_dwordx2 v[176:177], v202, s[8:9]
	s_add_u32 s8, s8, 0x1000
	s_addc_u32 s9, s9, 0
	global_load_dwordx2 v[178:179], v202, s[8:9]
	s_add_u32 s8, s8, 0x1000
	s_addc_u32 s9, s9, 0
	global_load_dwordx2 v[184:185], v202, s[8:9]
	s_add_u32 s8, s8, 0x1000
	s_addc_u32 s9, s9, 0
	global_load_dwordx2 v[186:187], v202, s[8:9]
	s_add_u32 s8, s8, 0x1000
	s_addc_u32 s9, s9, 0
	global_load_dwordx2 v[188:189], v202, s[8:9]
	s_add_u32 s8, s8, 0x1000
	s_addc_u32 s9, s9, 0
	global_load_dwordx2 v[190:191], v202, s[8:9]
	s_add_u32 s8, s8, 0x1000
	s_addc_u32 s9, s9, 0
	s_waitcnt vmcnt(0)
	v_pk_add_f32 v[80:81], v[80:81], v[156:157]
	v_pk_add_f32 v[78:79], v[78:79], v[158:159]
	v_pk_add_f32 v[76:77], v[76:77], v[160:161]
	v_pk_add_f32 v[74:75], v[74:75], v[162:163]
	v_pk_add_f32 v[72:73], v[72:73], v[164:165]
	v_pk_add_f32 v[70:71], v[70:71], v[166:167]
	v_pk_add_f32 v[68:69], v[68:69], v[168:169]
	v_pk_add_f32 v[66:67], v[66:67], v[170:171]
	v_pk_add_f32 v[60:61], v[60:61], v[172:173]
	v_pk_add_f32 v[58:59], v[58:59], v[174:175]
	v_pk_add_f32 v[52:53], v[52:53], v[176:177]
	v_pk_add_f32 v[50:51], v[50:51], v[178:179]
	v_pk_add_f32 v[44:45], v[44:45], v[184:185]
	v_pk_add_f32 v[42:43], v[42:43], v[186:187]
	v_pk_add_f32 v[40:41], v[40:41], v[188:189]
	v_pk_add_f32 v[38:39], v[38:39], v[190:191]
	global_load_dwordx2 v[156:157], v202, s[8:9]
	s_add_u32 s8, s8, 0x1000
	s_addc_u32 s9, s9, 0
	global_load_dwordx2 v[158:159], v202, s[8:9]
	s_add_u32 s8, s8, 0x1000
	s_addc_u32 s9, s9, 0
	global_load_dwordx2 v[160:161], v202, s[8:9]
	s_add_u32 s8, s8, 0x1000
	s_addc_u32 s9, s9, 0
	global_load_dwordx2 v[162:163], v202, s[8:9]
	s_add_u32 s8, s8, 0x1000
	s_addc_u32 s9, s9, 0
	global_load_dwordx2 v[164:165], v202, s[8:9]
	s_add_u32 s8, s8, 0x1000
	s_addc_u32 s9, s9, 0
	global_load_dwordx2 v[166:167], v202, s[8:9]
	s_add_u32 s8, s8, 0x1000
	s_addc_u32 s9, s9, 0
	global_load_dwordx2 v[168:169], v202, s[8:9]
	s_add_u32 s8, s8, 0x1000
	s_addc_u32 s9, s9, 0
	global_load_dwordx2 v[170:171], v202, s[8:9]
	s_add_u32 s8, s8, 0x1000
	s_addc_u32 s9, s9, 0
	global_load_dwordx2 v[172:173], v202, s[8:9]
	s_add_u32 s8, s8, 0x1000
	s_addc_u32 s9, s9, 0
	global_load_dwordx2 v[174:175], v202, s[8:9]
	s_add_u32 s8, s8, 0x1000
	s_addc_u32 s9, s9, 0
	global_load_dwordx2 v[176:177], v202, s[8:9]
	s_add_u32 s8, s8, 0x1000
	s_addc_u32 s9, s9, 0
	global_load_dwordx2 v[178:179], v202, s[8:9]
	s_add_u32 s8, s8, 0x1000
	s_addc_u32 s9, s9, 0
	global_load_dwordx2 v[184:185], v202, s[8:9]
	s_add_u32 s8, s8, 0x1000
	s_addc_u32 s9, s9, 0
	global_load_dwordx2 v[186:187], v202, s[8:9]
	s_add_u32 s8, s8, 0x1000
	s_addc_u32 s9, s9, 0
	global_load_dwordx2 v[188:189], v202, s[8:9]
	s_add_u32 s8, s8, 0x1000
	s_addc_u32 s9, s9, 0
	global_load_dwordx2 v[190:191], v202, s[8:9]
	s_add_u32 s8, s8, 0x1000
	s_addc_u32 s9, s9, 0
	s_waitcnt vmcnt(0)
	v_pk_add_f32 v[32:33], v[32:33], v[156:157]
	v_pk_add_f32 v[30:31], v[30:31], v[158:159]
	v_pk_add_f32 v[28:29], v[28:29], v[160:161]
	v_pk_add_f32 v[26:27], v[26:27], v[162:163]
	v_pk_add_f32 v[24:25], v[24:25], v[164:165]
	v_pk_add_f32 v[22:23], v[22:23], v[166:167]
	v_pk_add_f32 v[20:21], v[20:21], v[168:169]
	v_pk_add_f32 v[18:19], v[18:19], v[170:171]
	v_pk_add_f32 v[16:17], v[16:17], v[172:173]
	v_pk_add_f32 v[14:15], v[14:15], v[174:175]
	v_pk_add_f32 v[12:13], v[12:13], v[176:177]
	v_pk_add_f32 v[10:11], v[10:11], v[178:179]
	v_pk_add_f32 v[8:9], v[8:9], v[184:185]
	v_pk_add_f32 v[6:7], v[6:7], v[186:187]
	v_pk_add_f32 v[4:5], v[4:5], v[188:189]
	v_pk_add_f32 v[2:3], v[2:3], v[190:191]
	global_load_dwordx2 v[156:157], v202, s[8:9]
	s_add_u32 s8, s8, 0x1000
	s_addc_u32 s9, s9, 0
	global_load_dwordx2 v[158:159], v202, s[8:9]
	s_add_u32 s8, s8, 0x1000
	s_addc_u32 s9, s9, 0
	global_load_dwordx2 v[160:161], v202, s[8:9]
	s_add_u32 s8, s8, 0x1000
	s_addc_u32 s9, s9, 0
	global_load_dwordx2 v[162:163], v202, s[8:9]
	s_add_u32 s8, s8, 0x1000
	s_addc_u32 s9, s9, 0
	global_load_dwordx2 v[164:165], v202, s[8:9]
	s_add_u32 s8, s8, 0x1000
	s_addc_u32 s9, s9, 0
	global_load_dwordx2 v[166:167], v202, s[8:9]
	s_add_u32 s8, s8, 0x1000
	s_addc_u32 s9, s9, 0
	global_load_dwordx2 v[168:169], v202, s[8:9]
	s_add_u32 s8, s8, 0x1000
	s_addc_u32 s9, s9, 0
	global_load_dwordx2 v[170:171], v202, s[8:9]
	s_add_u32 s8, s8, 0x1000
	s_addc_u32 s9, s9, 0
	global_load_dwordx2 v[172:173], v202, s[8:9]
	s_add_u32 s8, s8, 0x1000
	s_addc_u32 s9, s9, 0
	global_load_dwordx2 v[174:175], v202, s[8:9]
	s_add_u32 s8, s8, 0x1000
	s_addc_u32 s9, s9, 0
	global_load_dwordx2 v[176:177], v202, s[8:9]
	s_add_u32 s8, s8, 0x1000
	s_addc_u32 s9, s9, 0
	global_load_dwordx2 v[178:179], v202, s[8:9]
	s_add_u32 s8, s8, 0x1000
	s_addc_u32 s9, s9, 0
	global_load_dwordx2 v[184:185], v202, s[8:9]
	s_add_u32 s8, s8, 0x1000
	s_addc_u32 s9, s9, 0
	global_load_dwordx2 v[186:187], v202, s[8:9]
	s_add_u32 s8, s8, 0x1000
	s_addc_u32 s9, s9, 0
	global_load_dwordx2 v[188:189], v202, s[8:9]
	s_add_u32 s8, s8, 0x1000
	s_addc_u32 s9, s9, 0
	global_load_dwordx2 v[190:191], v202, s[8:9]
	s_add_u32 s8, s8, 0x1000
	s_addc_u32 s9, s9, 0
	s_waitcnt vmcnt(0)
; template <class Epi, class SchedT>
; DI void gemm_phase(LAS unsigned char* lds, const Gemm g, const SchedT& S, const Epi& E) {
;     ...
;         { int fr2 = fr, fq2 = fq, wr2 = wr, wc2 = wc; asm volatile("" : "+v"(fr2), "+v"(fq2), "+s"(wr2), "+s"(wc2));
;           E(acc, cur, wr2, wc2, fr2, fq2); }
	v_pk_add_f32 v[144:145], v[144:145], v[156:157]
	v_pk_add_f32 v[142:143], v[142:143], v[158:159]
	v_pk_add_f32 v[140:141], v[140:141], v[160:161]
	v_pk_add_f32 v[138:139], v[138:139], v[162:163]
	v_pk_add_f32 v[136:137], v[136:137], v[164:165]
	v_pk_add_f32 v[134:135], v[134:135], v[166:167]
	v_pk_add_f32 v[132:133], v[132:133], v[168:169]
	v_pk_add_f32 v[130:131], v[130:131], v[170:171]
	v_pk_add_f32 v[128:129], v[128:129], v[172:173]
	v_pk_add_f32 v[126:127], v[126:127], v[174:175]
	v_pk_add_f32 v[124:125], v[124:125], v[176:177]
	v_pk_add_f32 v[122:123], v[122:123], v[178:179]
	v_pk_add_f32 v[120:121], v[120:121], v[184:185]
	v_pk_add_f32 v[118:119], v[118:119], v[186:187]
	v_pk_add_f32 v[116:117], v[116:117], v[188:189]
	v_pk_add_f32 v[114:115], v[114:115], v[190:191]
	global_load_dwordx2 v[156:157], v202, s[8:9]
	s_add_u32 s8, s8, 0x1000
	s_addc_u32 s9, s9, 0
	global_load_dwordx2 v[158:159], v202, s[8:9]
	s_add_u32 s8, s8, 0x1000
	s_addc_u32 s9, s9, 0
	global_load_dwordx2 v[160:161], v202, s[8:9]
	s_add_u32 s8, s8, 0x1000
	s_addc_u32 s9, s9, 0
	global_load_dwordx2 v[162:163], v202, s[8:9]
	s_add_u32 s8, s8, 0x1000
	s_addc_u32 s9, s9, 0
	global_load_dwordx2 v[164:165], v202, s[8:9]
	s_add_u32 s8, s8, 0x1000
	s_addc_u32 s9, s9, 0
	global_load_dwordx2 v[166:167], v202, s[8:9]
	s_add_u32 s8, s8, 0x1000
	s_addc_u32 s9, s9, 0
	global_load_dwordx2 v[168:169], v202, s[8:9]
	s_add_u32 s8, s8, 0x1000
	s_addc_u32 s9, s9, 0
	global_load_dwordx2 v[170:171], v202, s[8:9]
	s_add_u32 s8, s8, 0x1000
	s_addc_u32 s9, s9, 0
	global_load_dwordx2 v[172:173], v202, s[8:9]
	s_add_u32 s8, s8, 0x1000
	s_addc_u32 s9, s9, 0
	global_load_dwordx2 v[174:175], v202, s[8:9]
	s_add_u32 s8, s8, 0x1000
	s_addc_u32 s9, s9, 0
	global_load_dwordx2 v[176:177], v202, s[8:9]
	s_add_u32 s8, s8, 0x1000
	s_addc_u32 s9, s9, 0
	global_load_dwordx2 v[178:179], v202, s[8:9]
	s_add_u32 s8, s8, 0x1000
	s_addc_u32 s9, s9, 0
	global_load_dwordx2 v[184:185], v202, s[8:9]
	s_add_u32 s8, s8, 0x1000
	s_addc_u32 s9, s9, 0
	global_load_dwordx2 v[186:187], v202, s[8:9]
	s_add_u32 s8, s8, 0x1000
	s_addc_u32 s9, s9, 0
	global_load_dwordx2 v[188:189], v202, s[8:9]
	s_add_u32 s8, s8, 0x1000
	s_addc_u32 s9, s9, 0
	global_load_dwordx2 v[190:191], v202, s[8:9]
	s_add_u32 s8, s8, 0x1000
	s_addc_u32 s9, s9, 0
	s_waitcnt vmcnt(0)
	v_pk_add_f32 v[112:113], v[112:113], v[156:157]
	v_pk_add_f32 v[110:111], v[110:111], v[158:159]
	v_pk_add_f32 v[108:109], v[108:109], v[160:161]
	v_pk_add_f32 v[106:107], v[106:107], v[162:163]
	v_pk_add_f32 v[104:105], v[104:105], v[164:165]
	v_pk_add_f32 v[102:103], v[102:103], v[166:167]
	v_pk_add_f32 v[100:101], v[100:101], v[168:169]
	v_pk_add_f32 v[98:99], v[98:99], v[170:171]
	v_pk_add_f32 v[96:97], v[96:97], v[172:173]
	v_pk_add_f32 v[94:95], v[94:95], v[174:175]
	v_pk_add_f32 v[92:93], v[92:93], v[176:177]
	v_pk_add_f32 v[90:91], v[90:91], v[178:179]
	v_pk_add_f32 v[88:89], v[88:89], v[184:185]
	v_pk_add_f32 v[86:87], v[86:87], v[186:187]
	v_pk_add_f32 v[84:85], v[84:85], v[188:189]
	v_pk_add_f32 v[82:83], v[82:83], v[190:191]
	global_load_dwordx2 v[156:157], v202, s[8:9]
	s_add_u32 s8, s8, 0x1000
	s_addc_u32 s9, s9, 0
	global_load_dwordx2 v[158:159], v202, s[8:9]
	s_add_u32 s8, s8, 0x1000
	s_addc_u32 s9, s9, 0
	global_load_dwordx2 v[160:161], v202, s[8:9]
	s_add_u32 s8, s8, 0x1000
	s_addc_u32 s9, s9, 0
	global_load_dwordx2 v[162:163], v202, s[8:9]
	s_add_u32 s8, s8, 0x1000
	s_addc_u32 s9, s9, 0
	global_load_dwordx2 v[164:165], v202, s[8:9]
	s_add_u32 s8, s8, 0x1000
	s_addc_u32 s9, s9, 0
	global_load_dwordx2 v[166:167], v202, s[8:9]
	s_add_u32 s8, s8, 0x1000
	s_addc_u32 s9, s9, 0
	global_load_dwordx2 v[168:169], v202, s[8:9]
	s_add_u32 s8, s8, 0x1000
	s_addc_u32 s9, s9, 0
	global_load_dwordx2 v[170:171], v202, s[8:9]
	s_add_u32 s8, s8, 0x1000
	s_addc_u32 s9, s9, 0
	global_load_dwordx2 v[172:173], v202, s[8:9]
	s_add_u32 s8, s8, 0x1000
	s_addc_u32 s9, s9, 0
	global_load_dwordx2 v[174:175], v202, s[8:9]
	s_add_u32 s8, s8, 0x1000
	s_addc_u32 s9, s9, 0
	global_load_dwordx2 v[176:177], v202, s[8:9]
	s_add_u32 s8, s8, 0x1000
	s_addc_u32 s9, s9, 0
	global_load_dwordx2 v[178:179], v202, s[8:9]
	s_add_u32 s8, s8, 0x1000
	s_addc_u32 s9, s9, 0
	global_load_dwordx2 v[184:185], v202, s[8:9]
	s_add_u32 s8, s8, 0x1000
	s_addc_u32 s9, s9, 0
	global_load_dwordx2 v[186:187], v202, s[8:9]
	s_add_u32 s8, s8, 0x1000
	s_addc_u32 s9, s9, 0
	global_load_dwordx2 v[188:189], v202, s[8:9]
	s_add_u32 s8, s8, 0x1000
	s_addc_u32 s9, s9, 0
	global_load_dwordx2 v[190:191], v202, s[8:9]
	s_add_u32 s8, s8, 0x1000
	s_addc_u32 s9, s9, 0
	s_waitcnt vmcnt(0)
; DI unsigned pk2(float a, float b) { f32x2 v = {a, b}; bfv2 r = __builtin_convertvector(v, bfv2); return __builtin_bit_cast(unsigned, r); }
;     DI void operator()(AccRef acc, const Unit& u, int wr, int wc, int fr, int fq) const {
;         const int row0 = u.pm * 256; const int midx = row0 < ML ? (row0 >> 12) : 4;
;         const float* src = row0 < ML ? xl : (xc - (size_t)ML * D);
;         const float* gp = gate + (size_t)midx * 12288;
;         const int col0 = u.pn * 256 + wc * 32 + 4 * fq;
;         f32x4 gv[2][2];
; #pragma unroll
;         for (int bj = 0; bj < 2; ++bj)
; #pragma unroll
;             for (int n = 0; n < 2; ++n) gv[bj][n] = *(const f32x4*)(gp + col0 + bj * 128 + n * 16);
;         if (xb) {
; #pragma unroll
;             for (int ai = 0; ai < 2; ++ai)
; #pragma unroll
;                 for (int m = 0; m < 4; ++m) { const size_t off = (size_t)(row0 + wr * 64 + fr + ai * 128 + m * 16) * D + col0;
; #pragma unroll
;                     for (int bj = 0; bj < 2; ++bj)
; #pragma unroll
;                         for (int n = 0; n < 2; ++n) { const size_t o2 = off + bj * 128 + n * 16;
;                             const f32x4 r = bf4(*(const u32x2*)(xb + o2)) + gv[bj][n] * acc[ai][bj][m][n];
;                             u32x2 w; w.x = pk2(r[0], r[1]); w.y = pk2(r[2], r[3]); *(u32x2*)(out + o2) = w; }
;                     asm volatile("" ::: "memory"); }
	v_pk_add_f32 v[80:81], v[80:81], v[156:157]
	v_pk_add_f32 v[78:79], v[78:79], v[158:159]
	v_pk_add_f32 v[76:77], v[76:77], v[160:161]
	v_pk_add_f32 v[74:75], v[74:75], v[162:163]
	v_pk_add_f32 v[72:73], v[72:73], v[164:165]
	v_pk_add_f32 v[70:71], v[70:71], v[166:167]
	v_pk_add_f32 v[68:69], v[68:69], v[168:169]
	v_pk_add_f32 v[66:67], v[66:67], v[170:171]
	v_pk_add_f32 v[60:61], v[60:61], v[172:173]
	v_pk_add_f32 v[58:59], v[58:59], v[174:175]
	v_pk_add_f32 v[52:53], v[52:53], v[176:177]
	v_pk_add_f32 v[50:51], v[50:51], v[178:179]
	v_pk_add_f32 v[44:45], v[44:45], v[184:185]
	v_pk_add_f32 v[42:43], v[42:43], v[186:187]
	v_pk_add_f32 v[40:41], v[40:41], v[188:189]
	v_pk_add_f32 v[38:39], v[38:39], v[190:191]
	global_load_dwordx2 v[156:157], v202, s[8:9]
	s_add_u32 s8, s8, 0x1000
	s_addc_u32 s9, s9, 0
	global_load_dwordx2 v[158:159], v202, s[8:9]
	s_add_u32 s8, s8, 0x1000
	s_addc_u32 s9, s9, 0
	global_load_dwordx2 v[160:161], v202, s[8:9]
	s_add_u32 s8, s8, 0x1000
	s_addc_u32 s9, s9, 0
	global_load_dwordx2 v[162:163], v202, s[8:9]
	s_add_u32 s8, s8, 0x1000
	s_addc_u32 s9, s9, 0
	global_load_dwordx2 v[164:165], v202, s[8:9]
	s_add_u32 s8, s8, 0x1000
	s_addc_u32 s9, s9, 0
	global_load_dwordx2 v[166:167], v202, s[8:9]
	s_add_u32 s8, s8, 0x1000
	s_addc_u32 s9, s9, 0
	global_load_dwordx2 v[168:169], v202, s[8:9]
	s_add_u32 s8, s8, 0x1000
	s_addc_u32 s9, s9, 0
	global_load_dwordx2 v[170:171], v202, s[8:9]
	s_add_u32 s8, s8, 0x1000
	s_addc_u32 s9, s9, 0
	global_load_dwordx2 v[172:173], v202, s[8:9]
	s_add_u32 s8, s8, 0x1000
	s_addc_u32 s9, s9, 0
	global_load_dwordx2 v[174:175], v202, s[8:9]
	s_add_u32 s8, s8, 0x1000
	s_addc_u32 s9, s9, 0
	global_load_dwordx2 v[176:177], v202, s[8:9]
	s_add_u32 s8, s8, 0x1000
	s_addc_u32 s9, s9, 0
	global_load_dwordx2 v[178:179], v202, s[8:9]
	s_add_u32 s8, s8, 0x1000
	s_addc_u32 s9, s9, 0
	global_load_dwordx2 v[184:185], v202, s[8:9]
	s_add_u32 s8, s8, 0x1000
	s_addc_u32 s9, s9, 0
	global_load_dwordx2 v[186:187], v202, s[8:9]
	s_add_u32 s8, s8, 0x1000
	s_addc_u32 s9, s9, 0
	global_load_dwordx2 v[188:189], v202, s[8:9]
	s_add_u32 s8, s8, 0x1000
	s_addc_u32 s9, s9, 0
	global_load_dwordx2 v[190:191], v202, s[8:9]
	s_add_u32 s8, s8, 0x1000
	s_addc_u32 s9, s9, 0
	s_waitcnt vmcnt(0)
	v_pk_add_f32 v[32:33], v[32:33], v[156:157]
	v_pk_add_f32 v[30:31], v[30:31], v[158:159]
	v_pk_add_f32 v[28:29], v[28:29], v[160:161]
	v_pk_add_f32 v[26:27], v[26:27], v[162:163]
	v_pk_add_f32 v[24:25], v[24:25], v[164:165]
	v_pk_add_f32 v[22:23], v[22:23], v[166:167]
	v_pk_add_f32 v[20:21], v[20:21], v[168:169]
	v_pk_add_f32 v[18:19], v[18:19], v[170:171]
	v_pk_add_f32 v[16:17], v[16:17], v[172:173]
	v_pk_add_f32 v[14:15], v[14:15], v[174:175]
	v_pk_add_f32 v[12:13], v[12:13], v[176:177]
	v_pk_add_f32 v[10:11], v[10:11], v[178:179]
	v_pk_add_f32 v[8:9], v[8:9], v[184:185]
	v_pk_add_f32 v[6:7], v[6:7], v[186:187]
	v_pk_add_f32 v[4:5], v[4:5], v[188:189]
	v_pk_add_f32 v[2:3], v[2:3], v[190:191]
.Lq_epi_normal:
	s_min_i32 s8, s38, 64
	s_ashr_i32 s8, s8, 4
	v_mov_b32_e32 v0, v149
	s_mov_b32 s10, s30
	v_mov_b32_e32 v152, v148
	s_mov_b32 s11, s17
	s_lshl_b32 s12, s38, 8
	s_mul_hi_i32 s9, s8, 0xc000
	s_mul_i32 s8, s8, 0xc000
	s_add_u32 s8, s28, s8
	s_addc_u32 s9, s29, s9
	s_lshl_b32 s13, s33, 8
	s_lshl_b32 s10, s10, 5
	s_add_i32 s10, s10, s13
	v_lshl_add_u32 v146, v0, 2, s10
	v_ashrrev_i32_e32 v147, 31, v146
	v_lshl_add_u64 v[34:35], v[146:147], 2, s[8:9]
	s_lshl_b32 s8, s11, 6
	s_add_i32 s8, s8, s12
	v_add_u32_e32 v152, s8, v152
	v_ashrrev_i32_e32 v153, 31, v152
	v_lshlrev_b64 v[152:153], 12, v[152:153]
	v_lshl_add_u64 v[152:153], s[4:5], 0, v[152:153]
	v_lshl_add_u64 v[146:147], v[146:147], 1, v[152:153]
	global_load_dwordx4 v[62:65], v[34:35], off
	global_load_dwordx4 v[54:57], v[34:35], off offset:64
	global_load_dwordx4 v[46:49], v[34:35], off offset:512
	s_nop 0
	global_load_dwordx4 v[34:37], v[34:35], off offset:576
	s_mov_b64 s[8:9], 0x10000
	global_load_dwordx2 v[152:153], v[146:147], off
	global_load_dwordx2 v[206:207], v[146:147], off offset:32
	global_load_dwordx2 v[208:209], v[146:147], off offset:256
	global_load_dwordx2 v[210:211], v[146:147], off offset:288
	s_waitcnt vmcnt(3)
	v_lshlrev_b32_e32 v154, 16, v152
	v_and_b32_e32 v155, 0xffff0000, v152
	v_lshlrev_b32_e32 v152, 16, v153
	v_and_b32_e32 v153, 0xffff0000, v153
	v_pk_fma_f32 v[144:145], v[144:145], v[64:65], v[152:153]
	v_pk_fma_f32 v[142:143], v[142:143], v[62:63], v[154:155]
	s_nop 0
	v_cvt_pk_bf16_f32 v142, v142, v143
	v_cvt_pk_bf16_f32 v143, v144, v145
	global_store_dwordx2 v[146:147], v[142:143], off
	s_waitcnt vmcnt(3)
	v_lshlrev_b32_e32 v144, 16, v206
	v_and_b32_e32 v145, 0xffff0000, v206
	v_lshlrev_b32_e32 v142, 16, v207
	v_and_b32_e32 v143, 0xffff0000, v207
	v_pk_fma_f32 v[140:141], v[140:141], v[56:57], v[142:143]
	v_pk_fma_f32 v[138:139], v[138:139], v[54:55], v[144:145]
	s_nop 0
	v_cvt_pk_bf16_f32 v138, v138, v139
	v_cvt_pk_bf16_f32 v139, v140, v141
	global_store_dwordx2 v[146:147], v[138:139], off offset:32
	s_waitcnt vmcnt(3)
	v_lshlrev_b32_e32 v140, 16, v208
	v_and_b32_e32 v141, 0xffff0000, v208
	v_lshlrev_b32_e32 v138, 16, v209
	v_and_b32_e32 v139, 0xffff0000, v209
	v_pk_fma_f32 v[136:137], v[136:137], v[48:49], v[138:139]
	v_pk_fma_f32 v[134:135], v[134:135], v[46:47], v[140:141]
	s_nop 0
	v_cvt_pk_bf16_f32 v134, v134, v135
	v_cvt_pk_bf16_f32 v135, v136, v137
	global_store_dwordx2 v[146:147], v[134:135], off offset:256
	s_waitcnt vmcnt(3)
; DI unsigned pk2(float a, float b) { f32x2 v = {a, b}; bfv2 r = __builtin_convertvector(v, bfv2); return __builtin_bit_cast(unsigned, r); }
;     DI void operator()(AccRef acc, const Unit& u, int wr, int wc, int fr, int fq) const {
;     ...
;         if (xb) {
; #pragma unroll
;             for (int ai = 0; ai < 2; ++ai)
; #pragma unroll
;                 for (int m = 0; m < 4; ++m) { const size_t off = (size_t)(row0 + wr * 64 + fr + ai * 128 + m * 16) * D + col0;
; #pragma unroll
;                     for (int bj = 0; bj < 2; ++bj)
; #pragma unroll
;                         for (int n = 0; n < 2; ++n) { const size_t o2 = off + bj * 128 + n * 16;
;                             const f32x4 r = bf4(*(const u32x2*)(xb + o2)) + gv[bj][n] * acc[ai][bj][m][n];
;                             u32x2 w; w.x = pk2(r[0], r[1]); w.y = pk2(r[2], r[3]); *(u32x2*)(out + o2) = w; }
;                     asm volatile("" ::: "memory"); }
	v_lshlrev_b32_e32 v136, 16, v210
	v_and_b32_e32 v137, 0xffff0000, v210
	v_lshlrev_b32_e32 v134, 16, v211
	v_and_b32_e32 v135, 0xffff0000, v211
	v_pk_fma_f32 v[132:133], v[132:133], v[36:37], v[134:135]
	v_pk_fma_f32 v[130:131], v[130:131], v[34:35], v[136:137]
	s_nop 0
	v_cvt_pk_bf16_f32 v130, v130, v131
	v_cvt_pk_bf16_f32 v131, v132, v133
	global_store_dwordx2 v[146:147], v[130:131], off offset:288
	v_lshl_add_u64 v[130:131], v[146:147], 0, s[8:9]
	s_mov_b32 s8, 0x10000
	v_add_co_u32_e32 v132, vcc, s8, v146
	s_mov_b64 s[8:9], 0x20000
	s_nop 0
	v_addc_co_u32_e32 v133, vcc, 0, v147, vcc
	global_load_dwordx2 v[134:135], v[132:133], off
	global_load_dwordx2 v[206:207], v[130:131], off offset:32
	global_load_dwordx2 v[208:209], v[130:131], off offset:256
	global_load_dwordx2 v[210:211], v[130:131], off offset:288
	s_waitcnt vmcnt(3)
	v_lshlrev_b32_e32 v136, 16, v134
	v_and_b32_e32 v137, 0xffff0000, v134
	v_lshlrev_b32_e32 v134, 16, v135
	v_and_b32_e32 v135, 0xffff0000, v135
	v_pk_fma_f32 v[128:129], v[128:129], v[64:65], v[134:135]
	v_pk_fma_f32 v[126:127], v[126:127], v[62:63], v[136:137]
	s_nop 0
	v_cvt_pk_bf16_f32 v126, v126, v127
	v_cvt_pk_bf16_f32 v127, v128, v129
	global_store_dwordx2 v[132:133], v[126:127], off
	s_waitcnt vmcnt(3)
	v_lshlrev_b32_e32 v128, 16, v206
	v_and_b32_e32 v129, 0xffff0000, v206
	v_lshlrev_b32_e32 v126, 16, v207
	v_and_b32_e32 v127, 0xffff0000, v207
	v_pk_fma_f32 v[124:125], v[124:125], v[56:57], v[126:127]
	v_pk_fma_f32 v[122:123], v[122:123], v[54:55], v[128:129]
	s_nop 0
	v_cvt_pk_bf16_f32 v122, v122, v123
	v_cvt_pk_bf16_f32 v123, v124, v125
	global_store_dwordx2 v[130:131], v[122:123], off offset:32
	s_waitcnt vmcnt(3)
	v_lshlrev_b32_e32 v124, 16, v208
	v_and_b32_e32 v125, 0xffff0000, v208
	v_lshlrev_b32_e32 v122, 16, v209
	v_and_b32_e32 v123, 0xffff0000, v209
	v_pk_fma_f32 v[120:121], v[120:121], v[48:49], v[122:123]
	v_pk_fma_f32 v[118:119], v[118:119], v[46:47], v[124:125]
	s_nop 0
	v_cvt_pk_bf16_f32 v118, v118, v119
	v_cvt_pk_bf16_f32 v119, v120, v121
	global_store_dwordx2 v[130:131], v[118:119], off offset:256
	s_waitcnt vmcnt(3)
	v_lshlrev_b32_e32 v120, 16, v210
	v_and_b32_e32 v121, 0xffff0000, v210
	v_lshlrev_b32_e32 v118, 16, v211
	v_and_b32_e32 v119, 0xffff0000, v211
	v_pk_fma_f32 v[116:117], v[116:117], v[36:37], v[118:119]
	v_pk_fma_f32 v[114:115], v[114:115], v[34:35], v[120:121]
	s_nop 0
	v_cvt_pk_bf16_f32 v114, v114, v115
	v_cvt_pk_bf16_f32 v115, v116, v117
	global_store_dwordx2 v[130:131], v[114:115], off offset:288
	v_lshl_add_u64 v[114:115], v[146:147], 0, s[8:9]
	s_mov_b32 s8, 0x20000
	v_add_co_u32_e32 v116, vcc, s8, v146
	s_mov_b64 s[8:9], 0x30000
	s_nop 0
	v_addc_co_u32_e32 v117, vcc, 0, v147, vcc
	global_load_dwordx2 v[118:119], v[116:117], off
	global_load_dwordx2 v[206:207], v[114:115], off offset:32
	global_load_dwordx2 v[208:209], v[114:115], off offset:256
	global_load_dwordx2 v[210:211], v[114:115], off offset:288
	s_waitcnt vmcnt(3)
	v_lshlrev_b32_e32 v120, 16, v118
	v_and_b32_e32 v121, 0xffff0000, v118
	v_lshlrev_b32_e32 v118, 16, v119
	v_and_b32_e32 v119, 0xffff0000, v119
	v_pk_fma_f32 v[112:113], v[112:113], v[64:65], v[118:119]
	v_pk_fma_f32 v[110:111], v[110:111], v[62:63], v[120:121]
	s_nop 0
	v_cvt_pk_bf16_f32 v110, v110, v111
	v_cvt_pk_bf16_f32 v111, v112, v113
	global_store_dwordx2 v[116:117], v[110:111], off
	s_waitcnt vmcnt(3)
	v_lshlrev_b32_e32 v112, 16, v206
	v_and_b32_e32 v113, 0xffff0000, v206
	v_lshlrev_b32_e32 v110, 16, v207
	v_and_b32_e32 v111, 0xffff0000, v207
	v_pk_fma_f32 v[108:109], v[108:109], v[56:57], v[110:111]
	v_pk_fma_f32 v[106:107], v[106:107], v[54:55], v[112:113]
	s_nop 0
	v_cvt_pk_bf16_f32 v106, v106, v107
	v_cvt_pk_bf16_f32 v107, v108, v109
	global_store_dwordx2 v[114:115], v[106:107], off offset:32
	s_waitcnt vmcnt(3)
	v_lshlrev_b32_e32 v108, 16, v208
	v_and_b32_e32 v109, 0xffff0000, v208
	v_lshlrev_b32_e32 v106, 16, v209
	v_and_b32_e32 v107, 0xffff0000, v209
	v_pk_fma_f32 v[104:105], v[104:105], v[48:49], v[106:107]
	v_pk_fma_f32 v[102:103], v[102:103], v[46:47], v[108:109]
	s_nop 0
	v_cvt_pk_bf16_f32 v102, v102, v103
	v_cvt_pk_bf16_f32 v103, v104, v105
	global_store_dwordx2 v[114:115], v[102:103], off offset:256
	s_waitcnt vmcnt(3)
	v_lshlrev_b32_e32 v104, 16, v210
	v_and_b32_e32 v105, 0xffff0000, v210
	v_lshlrev_b32_e32 v102, 16, v211
	v_and_b32_e32 v103, 0xffff0000, v211
	v_pk_fma_f32 v[100:101], v[100:101], v[36:37], v[102:103]
	v_pk_fma_f32 v[98:99], v[98:99], v[34:35], v[104:105]
	s_nop 0
	v_cvt_pk_bf16_f32 v98, v98, v99
	v_cvt_pk_bf16_f32 v99, v100, v101
	global_store_dwordx2 v[114:115], v[98:99], off offset:288
	v_lshl_add_u64 v[98:99], v[146:147], 0, s[8:9]
	s_mov_b32 s8, 0x30000
	v_add_co_u32_e32 v100, vcc, s8, v146
	s_mov_b64 s[8:9], 0x80000
	s_nop 0
	v_addc_co_u32_e32 v101, vcc, 0, v147, vcc
	global_load_dwordx2 v[102:103], v[100:101], off
	global_load_dwordx2 v[206:207], v[98:99], off offset:32
	global_load_dwordx2 v[208:209], v[98:99], off offset:256
	global_load_dwordx2 v[210:211], v[98:99], off offset:288
	s_waitcnt vmcnt(3)
	v_lshlrev_b32_e32 v104, 16, v102
	v_and_b32_e32 v105, 0xffff0000, v102
	v_lshlrev_b32_e32 v102, 16, v103
	v_and_b32_e32 v103, 0xffff0000, v103
	v_pk_fma_f32 v[96:97], v[96:97], v[64:65], v[102:103]
	v_pk_fma_f32 v[94:95], v[94:95], v[62:63], v[104:105]
	s_nop 0
	v_cvt_pk_bf16_f32 v94, v94, v95
	v_cvt_pk_bf16_f32 v95, v96, v97
	global_store_dwordx2 v[100:101], v[94:95], off
	s_waitcnt vmcnt(3)
	v_lshlrev_b32_e32 v96, 16, v206
	v_and_b32_e32 v97, 0xffff0000, v206
	v_lshlrev_b32_e32 v94, 16, v207
	v_and_b32_e32 v95, 0xffff0000, v207
	v_pk_fma_f32 v[92:93], v[92:93], v[56:57], v[94:95]
	v_pk_fma_f32 v[90:91], v[90:91], v[54:55], v[96:97]
	s_nop 0
	v_cvt_pk_bf16_f32 v90, v90, v91
	v_cvt_pk_bf16_f32 v91, v92, v93
	global_store_dwordx2 v[98:99], v[90:91], off offset:32
	s_waitcnt vmcnt(3)
; DI unsigned pk2(float a, float b) { f32x2 v = {a, b}; bfv2 r = __builtin_convertvector(v, bfv2); return __builtin_bit_cast(unsigned, r); }
;     DI void operator()(AccRef acc, const Unit& u, int wr, int wc, int fr, int fq) const {
;     ...
;         if (xb) {
; #pragma unroll
;             for (int ai = 0; ai < 2; ++ai)
; #pragma unroll
;                 for (int m = 0; m < 4; ++m) { const size_t off = (size_t)(row0 + wr * 64 + fr + ai * 128 + m * 16) * D + col0;
; #pragma unroll
;                     for (int bj = 0; bj < 2; ++bj)
; #pragma unroll
;                         for (int n = 0; n < 2; ++n) { const size_t o2 = off + bj * 128 + n * 16;
;                             const f32x4 r = bf4(*(const u32x2*)(xb + o2)) + gv[bj][n] * acc[ai][bj][m][n];
;                             u32x2 w; w.x = pk2(r[0], r[1]); w.y = pk2(r[2], r[3]); *(u32x2*)(out + o2) = w; }
;                     asm volatile("" ::: "memory"); }
	v_lshlrev_b32_e32 v92, 16, v208
	v_and_b32_e32 v93, 0xffff0000, v208
	v_lshlrev_b32_e32 v90, 16, v209
	v_and_b32_e32 v91, 0xffff0000, v209
	v_pk_fma_f32 v[88:89], v[88:89], v[48:49], v[90:91]
	v_pk_fma_f32 v[86:87], v[86:87], v[46:47], v[92:93]
	s_nop 0
	v_cvt_pk_bf16_f32 v86, v86, v87
	v_cvt_pk_bf16_f32 v87, v88, v89
	global_store_dwordx2 v[98:99], v[86:87], off offset:256
	s_waitcnt vmcnt(3)
	v_lshlrev_b32_e32 v88, 16, v210
	v_and_b32_e32 v89, 0xffff0000, v210
	v_lshlrev_b32_e32 v86, 16, v211
	v_and_b32_e32 v87, 0xffff0000, v211
	v_pk_fma_f32 v[84:85], v[84:85], v[36:37], v[86:87]
	v_pk_fma_f32 v[82:83], v[82:83], v[34:35], v[88:89]
	s_nop 0
	v_cvt_pk_bf16_f32 v82, v82, v83
	v_cvt_pk_bf16_f32 v83, v84, v85
	global_store_dwordx2 v[98:99], v[82:83], off offset:288
	v_lshl_add_u64 v[82:83], v[146:147], 0, s[8:9]
	s_mov_b32 s8, 0x80000
	v_add_co_u32_e32 v84, vcc, s8, v146
	s_mov_b64 s[8:9], 0x90000
	s_nop 0
	v_addc_co_u32_e32 v85, vcc, 0, v147, vcc
	global_load_dwordx2 v[86:87], v[84:85], off
	global_load_dwordx2 v[206:207], v[82:83], off offset:32
	global_load_dwordx2 v[208:209], v[82:83], off offset:256
	global_load_dwordx2 v[210:211], v[82:83], off offset:288
	s_waitcnt vmcnt(3)
	v_lshlrev_b32_e32 v88, 16, v86
	v_and_b32_e32 v89, 0xffff0000, v86
	v_lshlrev_b32_e32 v86, 16, v87
	v_and_b32_e32 v87, 0xffff0000, v87
	v_pk_fma_f32 v[80:81], v[80:81], v[64:65], v[86:87]
	v_pk_fma_f32 v[78:79], v[78:79], v[62:63], v[88:89]
	s_nop 0
	v_cvt_pk_bf16_f32 v78, v78, v79
	v_cvt_pk_bf16_f32 v79, v80, v81
	global_store_dwordx2 v[84:85], v[78:79], off
	s_waitcnt vmcnt(3)
	v_lshlrev_b32_e32 v80, 16, v206
	v_and_b32_e32 v81, 0xffff0000, v206
	v_lshlrev_b32_e32 v78, 16, v207
	v_and_b32_e32 v79, 0xffff0000, v207
	v_pk_fma_f32 v[76:77], v[76:77], v[56:57], v[78:79]
	v_pk_fma_f32 v[74:75], v[74:75], v[54:55], v[80:81]
	s_nop 0
	v_cvt_pk_bf16_f32 v74, v74, v75
	v_cvt_pk_bf16_f32 v75, v76, v77
	global_store_dwordx2 v[82:83], v[74:75], off offset:32
	s_waitcnt vmcnt(3)
	v_lshlrev_b32_e32 v76, 16, v208
	v_and_b32_e32 v77, 0xffff0000, v208
	v_lshlrev_b32_e32 v74, 16, v209
	v_and_b32_e32 v75, 0xffff0000, v209
	v_pk_fma_f32 v[72:73], v[72:73], v[48:49], v[74:75]
	v_pk_fma_f32 v[70:71], v[70:71], v[46:47], v[76:77]
	s_nop 0
	v_cvt_pk_bf16_f32 v70, v70, v71
	v_cvt_pk_bf16_f32 v71, v72, v73
	global_store_dwordx2 v[82:83], v[70:71], off offset:256
	s_waitcnt vmcnt(3)
	v_lshlrev_b32_e32 v72, 16, v210
	v_and_b32_e32 v73, 0xffff0000, v210
	v_lshlrev_b32_e32 v70, 16, v211
	v_and_b32_e32 v71, 0xffff0000, v211
	v_pk_fma_f32 v[68:69], v[68:69], v[36:37], v[70:71]
	v_pk_fma_f32 v[66:67], v[66:67], v[34:35], v[72:73]
	s_nop 0
	v_cvt_pk_bf16_f32 v66, v66, v67
	v_cvt_pk_bf16_f32 v67, v68, v69
	global_store_dwordx2 v[82:83], v[66:67], off offset:288
	v_lshl_add_u64 v[66:67], v[146:147], 0, s[8:9]
	s_mov_b32 s8, 0x90000
	v_add_co_u32_e32 v68, vcc, s8, v146
	s_mov_b64 s[8:9], 0xa0000
	s_nop 0
	v_addc_co_u32_e32 v69, vcc, 0, v147, vcc
	global_load_dwordx2 v[70:71], v[68:69], off
	global_load_dwordx2 v[206:207], v[66:67], off offset:32
	global_load_dwordx2 v[208:209], v[66:67], off offset:256
	global_load_dwordx2 v[210:211], v[66:67], off offset:288
	s_waitcnt vmcnt(3)
	v_lshlrev_b32_e32 v72, 16, v70
	v_and_b32_e32 v73, 0xffff0000, v70
	v_lshlrev_b32_e32 v70, 16, v71
	v_and_b32_e32 v71, 0xffff0000, v71
	v_pk_fma_f32 v[60:61], v[60:61], v[64:65], v[70:71]
	v_pk_fma_f32 v[58:59], v[58:59], v[62:63], v[72:73]
	s_nop 0
	v_cvt_pk_bf16_f32 v58, v58, v59
	v_cvt_pk_bf16_f32 v59, v60, v61
	global_store_dwordx2 v[68:69], v[58:59], off
	s_waitcnt vmcnt(3)
	v_lshlrev_b32_e32 v60, 16, v206
	v_and_b32_e32 v61, 0xffff0000, v206
	v_lshlrev_b32_e32 v58, 16, v207
	v_and_b32_e32 v59, 0xffff0000, v207
	v_pk_fma_f32 v[52:53], v[52:53], v[56:57], v[58:59]
	v_pk_fma_f32 v[50:51], v[50:51], v[54:55], v[60:61]
	s_nop 0
	v_cvt_pk_bf16_f32 v50, v50, v51
	v_cvt_pk_bf16_f32 v51, v52, v53
	global_store_dwordx2 v[66:67], v[50:51], off offset:32
	s_waitcnt vmcnt(3)
	v_lshlrev_b32_e32 v52, 16, v208
	v_and_b32_e32 v53, 0xffff0000, v208
	v_lshlrev_b32_e32 v50, 16, v209
	v_and_b32_e32 v51, 0xffff0000, v209
	v_pk_fma_f32 v[44:45], v[44:45], v[48:49], v[50:51]
	v_pk_fma_f32 v[42:43], v[42:43], v[46:47], v[52:53]
	s_nop 0
	v_cvt_pk_bf16_f32 v42, v42, v43
	v_cvt_pk_bf16_f32 v43, v44, v45
	global_store_dwordx2 v[66:67], v[42:43], off offset:256
	s_waitcnt vmcnt(3)
; DI unsigned pk2(float a, float b) { f32x2 v = {a, b}; bfv2 r = __builtin_convertvector(v, bfv2); return __builtin_bit_cast(unsigned, r); }
;     DI void operator()(AccRef acc, const Unit& u, int wr, int wc, int fr, int fq) const {
;     ...
;         if (xb) {
; #pragma unroll
;             for (int ai = 0; ai < 2; ++ai)
; #pragma unroll
;                 for (int m = 0; m < 4; ++m) { const size_t off = (size_t)(row0 + wr * 64 + fr + ai * 128 + m * 16) * D + col0;
; #pragma unroll
;                     for (int bj = 0; bj < 2; ++bj)
; #pragma unroll
;                         for (int n = 0; n < 2; ++n) { const size_t o2 = off + bj * 128 + n * 16;
;                             const f32x4 r = bf4(*(const u32x2*)(xb + o2)) + gv[bj][n] * acc[ai][bj][m][n];
;                             u32x2 w; w.x = pk2(r[0], r[1]); w.y = pk2(r[2], r[3]); *(u32x2*)(out + o2) = w; }
;                     asm volatile("" ::: "memory"); }
	v_lshlrev_b32_e32 v44, 16, v210
	v_and_b32_e32 v45, 0xffff0000, v210
	v_lshlrev_b32_e32 v42, 16, v211
	v_and_b32_e32 v43, 0xffff0000, v211
	v_pk_fma_f32 v[40:41], v[40:41], v[36:37], v[42:43]
	v_pk_fma_f32 v[38:39], v[38:39], v[34:35], v[44:45]
	s_nop 0
	v_cvt_pk_bf16_f32 v38, v38, v39
	v_cvt_pk_bf16_f32 v39, v40, v41
	global_store_dwordx2 v[66:67], v[38:39], off offset:288
	v_lshl_add_u64 v[38:39], v[146:147], 0, s[8:9]
	s_mov_b32 s8, 0xa0000
	v_add_co_u32_e32 v40, vcc, s8, v146
	s_mov_b64 s[8:9], 0xb0000
	s_nop 0
	v_addc_co_u32_e32 v41, vcc, 0, v147, vcc
	global_load_dwordx2 v[42:43], v[40:41], off
	global_load_dwordx2 v[206:207], v[38:39], off offset:32
	global_load_dwordx2 v[208:209], v[38:39], off offset:256
	global_load_dwordx2 v[210:211], v[38:39], off offset:288
	s_waitcnt vmcnt(3)
	v_lshlrev_b32_e32 v44, 16, v42
	v_and_b32_e32 v45, 0xffff0000, v42
	v_lshlrev_b32_e32 v42, 16, v43
	v_and_b32_e32 v43, 0xffff0000, v43
	v_pk_fma_f32 v[32:33], v[32:33], v[64:65], v[42:43]
	v_pk_fma_f32 v[30:31], v[30:31], v[62:63], v[44:45]
	s_nop 0
	v_cvt_pk_bf16_f32 v30, v30, v31
	v_cvt_pk_bf16_f32 v31, v32, v33
	global_store_dwordx2 v[40:41], v[30:31], off
	s_waitcnt vmcnt(3)
	v_lshlrev_b32_e32 v32, 16, v206
	v_and_b32_e32 v33, 0xffff0000, v206
	v_lshlrev_b32_e32 v30, 16, v207
	v_and_b32_e32 v31, 0xffff0000, v207
	v_pk_fma_f32 v[28:29], v[28:29], v[56:57], v[30:31]
	v_pk_fma_f32 v[26:27], v[26:27], v[54:55], v[32:33]
	s_nop 0
	v_cvt_pk_bf16_f32 v26, v26, v27
	v_cvt_pk_bf16_f32 v27, v28, v29
	global_store_dwordx2 v[38:39], v[26:27], off offset:32
	s_waitcnt vmcnt(3)
	v_lshlrev_b32_e32 v28, 16, v208
	v_and_b32_e32 v29, 0xffff0000, v208
	v_lshlrev_b32_e32 v26, 16, v209
	v_and_b32_e32 v27, 0xffff0000, v209
	v_pk_fma_f32 v[24:25], v[24:25], v[48:49], v[26:27]
	v_pk_fma_f32 v[22:23], v[22:23], v[46:47], v[28:29]
	s_nop 0
	v_cvt_pk_bf16_f32 v22, v22, v23
	v_cvt_pk_bf16_f32 v23, v24, v25
	global_store_dwordx2 v[38:39], v[22:23], off offset:256
	s_waitcnt vmcnt(3)
	v_lshlrev_b32_e32 v24, 16, v210
	v_and_b32_e32 v25, 0xffff0000, v210
	v_lshlrev_b32_e32 v22, 16, v211
	v_and_b32_e32 v23, 0xffff0000, v211
	v_pk_fma_f32 v[20:21], v[20:21], v[36:37], v[22:23]
	v_pk_fma_f32 v[18:19], v[18:19], v[34:35], v[24:25]
	s_nop 0
	v_cvt_pk_bf16_f32 v18, v18, v19
	v_cvt_pk_bf16_f32 v19, v20, v21
	global_store_dwordx2 v[38:39], v[18:19], off offset:288
	v_lshl_add_u64 v[18:19], v[146:147], 0, s[8:9]
	s_mov_b32 s8, 0xb0000
	v_add_co_u32_e32 v20, vcc, s8, v146
	s_mov_b64 s[8:9], -1
	s_nop 0
	v_addc_co_u32_e32 v21, vcc, 0, v147, vcc
	global_load_dwordx2 v[22:23], v[20:21], off
	global_load_dwordx2 v[206:207], v[18:19], off offset:32
	global_load_dwordx2 v[208:209], v[18:19], off offset:256
	global_load_dwordx2 v[210:211], v[18:19], off offset:288
	s_and_b64 vcc, exec, s[2:3]
	s_waitcnt vmcnt(3)
	v_lshlrev_b32_e32 v24, 16, v22
	v_and_b32_e32 v25, 0xffff0000, v22
	v_lshlrev_b32_e32 v22, 16, v23
	v_and_b32_e32 v23, 0xffff0000, v23
	v_pk_fma_f32 v[16:17], v[16:17], v[64:65], v[22:23]
	v_pk_fma_f32 v[14:15], v[14:15], v[62:63], v[24:25]
	s_nop 0
	v_cvt_pk_bf16_f32 v14, v14, v15
	v_cvt_pk_bf16_f32 v15, v16, v17
	global_store_dwordx2 v[20:21], v[14:15], off
	s_waitcnt vmcnt(3)
	v_lshlrev_b32_e32 v16, 16, v206
	v_and_b32_e32 v17, 0xffff0000, v206
	v_lshlrev_b32_e32 v14, 16, v207
	v_and_b32_e32 v15, 0xffff0000, v207
	v_pk_fma_f32 v[12:13], v[12:13], v[56:57], v[14:15]
	v_pk_fma_f32 v[10:11], v[10:11], v[54:55], v[16:17]
	s_nop 0
	v_cvt_pk_bf16_f32 v10, v10, v11
	v_cvt_pk_bf16_f32 v11, v12, v13
	global_store_dwordx2 v[18:19], v[10:11], off offset:32
	s_waitcnt vmcnt(3)
	v_lshlrev_b32_e32 v12, 16, v208
	v_and_b32_e32 v13, 0xffff0000, v208
	v_lshlrev_b32_e32 v10, 16, v209
	v_and_b32_e32 v11, 0xffff0000, v209
	v_pk_fma_f32 v[8:9], v[8:9], v[48:49], v[10:11]
	v_pk_fma_f32 v[6:7], v[6:7], v[46:47], v[12:13]
	s_nop 0
	v_cvt_pk_bf16_f32 v6, v6, v7
	v_cvt_pk_bf16_f32 v7, v8, v9
	global_store_dwordx2 v[18:19], v[6:7], off offset:256
	s_waitcnt vmcnt(3)
	v_lshlrev_b32_e32 v8, 16, v210
	v_and_b32_e32 v9, 0xffff0000, v210
	v_lshlrev_b32_e32 v6, 16, v211
	v_and_b32_e32 v7, 0xffff0000, v211
	v_pk_fma_f32 v[4:5], v[4:5], v[36:37], v[6:7]
	v_pk_fma_f32 v[2:3], v[2:3], v[34:35], v[8:9]
	s_nop 0
	v_cvt_pk_bf16_f32 v2, v2, v3
	v_cvt_pk_bf16_f32 v3, v4, v5
	global_store_dwordx2 v[18:19], v[2:3], off offset:288
